# retention group-norm pass requests the next batch of tiles before consuming the current one; compressed-attention row-max pass: hand-written loop with two K tiles in flight for the far key blocks (sin
# speedup vs baseline: 1.2449x; 1.0084x over previous
.LBB0_568:
	s_and_b32 s56, s55, 1
	s_lshl_b32 s57, s0, 4
	s_cmp_lt_i32 s0, 1
	v_cndmask_b32_e64 v141, 0, 1, s[26:27]
	s_cbranch_scc1 .LBB0_625
	s_lshl_b32 s60, s56, 3
	v_or_b32_e32 v64, s57, v79
	s_add_i32 s60, s60, s40
	v_lshlrev_b64 v[0:1], 11, v[64:65]
	s_lshl_b32 s16, s60, 6
	v_lshl_add_u64 v[0:1], s[22:23], 0, v[0:1]
	s_ashr_i32 s17, s16, 31
	v_lshl_add_u64 v[0:1], s[16:17], 1, v[0:1]
	v_mov_b32_e32 v85, v65
	s_lshl_b32 s52, s56, 17
	v_lshl_add_u64 v[0:1], v[0:1], 0, v[84:85]
	v_lshl_add_u64 v[88:89], v[76:77], 0, s[52:53]
	flat_load_dwordx4 v[8:11], v[0:1]
	flat_load_dwordx4 v[12:15], v[0:1] offset:64
	flat_load_dwordx4 v[16:19], v[88:89]
	flat_load_dwordx4 v[20:23], v[88:89] offset:1024
	flat_load_dwordx4 v[24:27], v[88:89] offset:2048
	flat_load_dwordx4 v[28:31], v[88:89] offset:3072
	s_min_i32 s0, s0, 0x3ff
	s_add_i32 s0, s0, 31
	s_ashr_i32 s61, s0, 5
	s_lshl_b32 s0, s60, 2
	s_add_i32 s62, s0, 0
	s_add_i32 s62, s62, 0x20400
	s_cmp_gt_i32 s61, 0
	s_cselect_b64 s[0:1], -1, 0
	s_cmp_lt_i32 s61, 1
	s_cbranch_scc1 .LBB0_596
	s_add_i32 s63, s57, 0xfffffdf1
	s_mov_b32 s76, 0
	v_mov_b32_e32 v41, 0
	v_mov_b32_e32 v42, 0xf149f2ca
	v_mov_b32_e32 v40, v138
	s_add_i32 s88, s63, 0xfffff9c0
	s_ashr_i32 s88, s88, 9
	s_add_i32 s88, s88, 1
	s_max_i32 s88, s88, 0
	s_add_i32 s89, s61, -1
	s_min_i32 s88, s88, s89
	s_min_i32 s88, s88, 31
	s_cmp_lt_i32 s88, 1
	s_cbranch_scc1 .Lcp1_done
	s_mov_b32 s86, 0x3fb8aa3b
	s_mov_b32 s87, 0x3fb8aa3b
	s_add_i32 s90, s62, 0x7c0
	v_mov_b32_e32 v170, s90
	ds_read_b32 v168, v170
	s_min_i32 s90, 1, s89
	s_lshl_b32 s90, s90, 12
	s_mov_b32 s91, 0
	v_lshl_add_u64 v[166:167], v[88:89], 0, s[90:91]
	global_load_dwordx4 v[150:153], v[166:167], off offset:0
	global_load_dwordx4 v[154:157], v[166:167], off offset:1024
	global_load_dwordx4 v[158:161], v[166:167], off offset:2048
	global_load_dwordx4 v[162:165], v[166:167], off offset:3072
.Lcp1_A:
	s_waitcnt vmcnt(4) lgkmcnt(0)
	v_mfma_f32_16x16x32_bf16 v[36:39], v[16:19], v[8:11], 0
	v_mfma_f32_16x16x32_bf16 v[4:7], v[24:27], v[8:11], 0
	v_mfma_f32_16x16x32_bf16 v[32:35], v[20:23], v[12:15], v[36:39]
	v_mfma_f32_16x16x32_bf16 v[36:39], v[28:31], v[12:15], v[4:7]
	s_cmp_lt_i32 s88, 2
	s_cbranch_scc1 .Lcp1_A_nopf
	s_add_i32 s90, s76, 2
	s_min_i32 s90, s90, s89
	s_lshl_b32 s90, s90, 12
	v_lshl_add_u64 v[166:167], v[88:89], 0, s[90:91]
	global_load_dwordx4 v[16:19], v[166:167], off offset:0
	global_load_dwordx4 v[20:23], v[166:167], off offset:1024
	global_load_dwordx4 v[24:27], v[166:167], off offset:2048
	global_load_dwordx4 v[28:31], v[166:167], off offset:3072
	s_branch .Lcp1_A_go

.Lcp1_A_go:
	s_nop 7
	v_pk_fma_f32 v[0:1], v[32:33], s[70:71], v[168:169] op_sel_hi:[1,0,0]
	v_pk_fma_f32 v[2:3], v[34:35], s[70:71], v[168:169] op_sel_hi:[1,0,0]
	v_pk_fma_f32 v[4:5], v[36:37], s[70:71], v[168:169] op_sel_hi:[1,0,0]
	v_pk_fma_f32 v[6:7], v[38:39], s[70:71], v[168:169] op_sel_hi:[1,0,0]
	v_max3_f32 v170, v0, v1, v2
	v_max3_f32 v171, v3, v4, v5
	v_max3_f32 v170, v170, v6, v7
	v_max3_f32 v170, v170, v171, v42
	v_mul_f32_e32 v172, 0xbfb8aa3b, v170
	v_sub_f32_e32 v173, v42, v170
	v_mul_f32_e32 v173, 0x3fb8aa3b, v173
	v_exp_f32_e32 v173, v173
	v_pk_fma_f32 v[0:1], v[0:1], s[86:87], v[172:173] op_sel_hi:[1,0,0]
	v_pk_fma_f32 v[2:3], v[2:3], s[86:87], v[172:173] op_sel_hi:[1,0,0]
	v_pk_fma_f32 v[4:5], v[4:5], s[86:87], v[172:173] op_sel_hi:[1,0,0]
	v_pk_fma_f32 v[6:7], v[6:7], s[86:87], v[172:173] op_sel_hi:[1,0,0]
	v_exp_f32_e32 v0, v0
	v_exp_f32_e32 v1, v1
	v_exp_f32_e32 v2, v2
	v_exp_f32_e32 v3, v3
	v_exp_f32_e32 v4, v4
	v_exp_f32_e32 v5, v5
	v_exp_f32_e32 v6, v6
	v_exp_f32_e32 v7, v7
	s_nop 0
	v_pk_add_f32 v[0:1], v[0:1], v[2:3]
	v_pk_add_f32 v[4:5], v[4:5], v[6:7]
	v_pk_add_f32 v[0:1], v[0:1], v[4:5]
	v_add_f32_e32 v0, v0, v1
	v_fmac_f32_e32 v0, v41, v173
	v_mov_b32_e32 v42, v170
	v_mov_b32_e32 v41, v0
	s_add_i32 s76, s76, 1
	s_addk_i32 s63, 0xfe00
	v_add_u32_e32 v40, 32, v40
	s_add_i32 s88, s88, -1
	s_cmp_lt_i32 s88, 1
	s_cbranch_scc1 .Lcp1_endA
.Lcp1_B:
	s_waitcnt vmcnt(4) lgkmcnt(0)
	v_mfma_f32_16x16x32_bf16 v[36:39], v[150:153], v[8:11], 0
	v_mfma_f32_16x16x32_bf16 v[4:7], v[158:161], v[8:11], 0
	v_mfma_f32_16x16x32_bf16 v[32:35], v[154:157], v[12:15], v[36:39]
	v_mfma_f32_16x16x32_bf16 v[36:39], v[162:165], v[12:15], v[4:7]
	s_cmp_lt_i32 s88, 2
	s_cbranch_scc1 .Lcp1_B_nopf
	s_add_i32 s90, s76, 2
	s_min_i32 s90, s90, s89
	s_lshl_b32 s90, s90, 12
	v_lshl_add_u64 v[166:167], v[88:89], 0, s[90:91]
	global_load_dwordx4 v[150:153], v[166:167], off offset:0
	global_load_dwordx4 v[154:157], v[166:167], off offset:1024
	global_load_dwordx4 v[158:161], v[166:167], off offset:2048
	global_load_dwordx4 v[162:165], v[166:167], off offset:3072
	s_branch .Lcp1_B_go

.Lcp1_B_go:
	s_nop 7
	v_pk_fma_f32 v[0:1], v[32:33], s[70:71], v[168:169] op_sel_hi:[1,0,0]
	v_pk_fma_f32 v[2:3], v[34:35], s[70:71], v[168:169] op_sel_hi:[1,0,0]
	v_pk_fma_f32 v[4:5], v[36:37], s[70:71], v[168:169] op_sel_hi:[1,0,0]
	v_pk_fma_f32 v[6:7], v[38:39], s[70:71], v[168:169] op_sel_hi:[1,0,0]
	v_max3_f32 v170, v0, v1, v2
	v_max3_f32 v171, v3, v4, v5
	v_max3_f32 v170, v170, v6, v7
	v_max3_f32 v170, v170, v171, v42
	v_mul_f32_e32 v172, 0xbfb8aa3b, v170
	v_sub_f32_e32 v173, v42, v170
	v_mul_f32_e32 v173, 0x3fb8aa3b, v173
	v_exp_f32_e32 v173, v173
	v_pk_fma_f32 v[0:1], v[0:1], s[86:87], v[172:173] op_sel_hi:[1,0,0]
	v_pk_fma_f32 v[2:3], v[2:3], s[86:87], v[172:173] op_sel_hi:[1,0,0]
	v_pk_fma_f32 v[4:5], v[4:5], s[86:87], v[172:173] op_sel_hi:[1,0,0]
	v_pk_fma_f32 v[6:7], v[6:7], s[86:87], v[172:173] op_sel_hi:[1,0,0]
	v_exp_f32_e32 v0, v0
	v_exp_f32_e32 v1, v1
	v_exp_f32_e32 v2, v2
	v_exp_f32_e32 v3, v3
	v_exp_f32_e32 v4, v4
	v_exp_f32_e32 v5, v5
	v_exp_f32_e32 v6, v6
	v_exp_f32_e32 v7, v7
	s_nop 0
	v_pk_add_f32 v[0:1], v[0:1], v[2:3]
	v_pk_add_f32 v[4:5], v[4:5], v[6:7]
	v_pk_add_f32 v[0:1], v[0:1], v[4:5]
	v_add_f32_e32 v0, v0, v1
	v_fmac_f32_e32 v0, v41, v173
	v_mov_b32_e32 v42, v170
	v_mov_b32_e32 v41, v0
	s_add_i32 s76, s76, 1
	s_addk_i32 s63, 0xfe00
	v_add_u32_e32 v40, 32, v40
	s_add_i32 s88, s88, -1
	s_cmp_lt_i32 s88, 1
	s_cbranch_scc0 .Lcp1_A
	s_branch .Lcp1_done
.Lcp1_endA:
	s_waitcnt vmcnt(0)
	v_mov_b32_e32 v16, v150
	v_mov_b32_e32 v17, v151
	v_mov_b32_e32 v18, v152
	v_mov_b32_e32 v19, v153
	v_mov_b32_e32 v20, v154
	v_mov_b32_e32 v21, v155
	v_mov_b32_e32 v22, v156
	v_mov_b32_e32 v23, v157
	v_mov_b32_e32 v24, v158
	v_mov_b32_e32 v25, v159
	v_mov_b32_e32 v26, v160
	v_mov_b32_e32 v27, v161
	v_mov_b32_e32 v28, v162
	v_mov_b32_e32 v29, v163
	v_mov_b32_e32 v30, v164
	v_mov_b32_e32 v31, v165
.Lcp1_done:
.LBB0_571:
	s_mov_b32 s4, s76
	s_add_i32 s76, s76, 1
	s_cmp_lt_i32 s76, s61
	s_cselect_b32 s52, s76, s4
	s_waitcnt vmcnt(0) lgkmcnt(0)
	v_mov_b64_e32 v[0:1], v[28:29]
	s_lshl_b64 s[2:3], s[52:53], 12
	v_mov_b64_e32 v[2:3], v[30:31]
	v_mov_b64_e32 v[4:5], v[24:25]
	v_mov_b64_e32 v[34:35], v[22:23]
	v_mov_b64_e32 v[38:39], v[18:19]
	v_lshl_add_u64 v[28:29], v[88:89], 0, s[2:3]
	v_mov_b64_e32 v[6:7], v[26:27]
	v_mov_b64_e32 v[32:33], v[20:21]
	v_mov_b64_e32 v[36:37], v[16:17]
	flat_load_dwordx4 v[16:19], v[28:29]
	flat_load_dwordx4 v[20:23], v[28:29] offset:1024
	flat_load_dwordx4 v[24:27], v[28:29] offset:2048
	s_nop 0
	flat_load_dwordx4 v[28:31], v[28:29] offset:3072
	v_mfma_f32_16x16x32_bf16 v[36:39], v[36:39], v[8:11], 0
	s_max_i32 s2, s63, 0
	s_cmp_lt_i32 s63, 16
	s_cselect_b64 vcc, -1, 0
	v_mfma_f32_16x16x32_bf16 v[4:7], v[4:7], v[8:11], 0
	s_cmp_lt_i32 s63, 0
	s_mov_b64 s[36:37], 0
	v_mfma_f32_16x16x32_bf16 v[32:35], v[32:35], v[12:15], v[36:39]
	v_mfma_f32_16x16x32_bf16 v[36:39], v[0:3], v[12:15], v[4:7]
	v_cvt_f32_u32_e32 v0, s2
	v_mov_b32_e32 v1, s2
	s_cselect_b64 s[2:3], -1, 0
	s_cmp_gt_u32 s4, 30
	v_mul_f32_e32 v0, 0x3d800000, v0
	v_log_f32_e32 v0, v0
	s_cselect_b64 s[4:5], -1, 0
	s_or_b64 s[2:3], s[2:3], s[4:5]
	v_mul_f32_e32 v0, 0x40124925, v0
	v_cvt_i32_f32_e32 v0, v0
	v_min_i32_e32 v0, 15, v0
	v_add_u32_e32 v0, 16, v0
	v_cndmask_b32_e32 v0, v0, v1, vcc
	s_and_b64 vcc, exec, s[2:3]
	v_readfirstlane_b32 s52, v0
	s_cbranch_vccnz .LBB0_573
	s_add_i32 s2, s63, 0x1ff
	v_cvt_f32_u32_e32 v0, s2
	s_mov_b64 s[36:37], -1
	v_mul_f32_e32 v0, 0x3d800000, v0
	v_log_f32_e32 v0, v0
	s_nop 0
	v_mul_f32_e32 v0, 0x40124925, v0
	v_cvt_i32_f32_e32 v0, v0
	v_min_i32_e32 v0, 15, v0
	s_nop 0
	v_readfirstlane_b32 s2, v0
	s_add_i32 s2, s2, 16
	s_cmp_lg_u32 s52, s2
	s_cselect_b64 s[2:3], -1, 0

.Lintra_c_go:
	v_mov_b32_e32 v221, v208
	v_and_b32_e32 v221, 63, v221
	v_lshlrev_b32_e32 v221, 2, v221
	v_xor_b32_e32 v222, 64, v221
	v_xor_b32_e32 v221, 0x80, v221
	ds_bpermute_b32 v223, v222, v202
	ds_bpermute_b32 v224, v222, v203
	s_waitcnt lgkmcnt(0)
	v_add_f32_e32 v202, v202, v223
	v_add_f32_e32 v203, v203, v224
	ds_bpermute_b32 v223, v221, v202
	ds_bpermute_b32 v224, v221, v203
	s_waitcnt lgkmcnt(0)
	v_add_f32_e32 v202, v202, v223
	v_add_f32_e32 v203, v203, v224
	v_mul_f32_e32 v227, 0x3b000000, v202
	v_mul_f32_e32 v228, 0x3b000000, v203
	v_fma_f32 v228, -v227, v227, v228
	v_max_f32_e32 v228, 0, v228
	v_add_f32_e32 v228, 0x3727c5ac, v228
	v_rsq_f32_e32 v228, v228
	s_mul_i32 s0, s8, 0x1800
	s_add_u32 s30, s20, s0
	s_addc_u32 s31, s21, 0
	s_lshl_b32 s0, s8, 12
	s_add_u32 s34, s22, s0
	s_addc_u32 s35, s23, 0
	s_waitcnt vmcnt(0)
	global_load_dwordx2 v[24:25], v205, s[34:35] offset:0
	global_load_dwordx2 v[100:101], v204, s[30:31] offset:0
	global_load_dwordx4 v[68:71], v206, s[28:29] offset:0
	global_load_dwordx2 v[26:27], v205, s[34:35] offset:32
	global_load_dwordx2 v[102:103], v204, s[30:31] offset:32
	global_load_dwordx4 v[72:75], v206, s[28:29] offset:64
	global_load_dwordx2 v[28:29], v205, s[34:35] offset:64
	global_load_dwordx2 v[104:105], v204, s[30:31] offset:64
	global_load_dwordx4 v[76:79], v206, s[28:29] offset:128
	global_load_dwordx2 v[30:31], v205, s[34:35] offset:96
	global_load_dwordx2 v[106:107], v204, s[30:31] offset:96
	global_load_dwordx4 v[80:83], v206, s[28:29] offset:192
	global_load_dwordx2 v[32:33], v205, s[34:35] offset:128
	global_load_dwordx2 v[108:109], v204, s[30:31] offset:128
	global_load_dwordx4 v[84:87], v206, s[28:29] offset:256
	global_load_dwordx2 v[34:35], v205, s[34:35] offset:160
	global_load_dwordx2 v[110:111], v204, s[30:31] offset:160
	global_load_dwordx4 v[88:91], v206, s[28:29] offset:320
	global_load_dwordx2 v[36:37], v205, s[34:35] offset:192
	global_load_dwordx2 v[112:113], v204, s[30:31] offset:192
	global_load_dwordx4 v[92:95], v206, s[28:29] offset:384
	global_load_dwordx2 v[38:39], v205, s[34:35] offset:224
	global_load_dwordx2 v[114:115], v204, s[30:31] offset:224
	global_load_dwordx4 v[96:99], v206, s[28:29] offset:448
	global_load_dwordx2 v[40:41], v205, s[34:35] offset:256
	global_load_dwordx2 v[116:117], v204, s[30:31] offset:256
	global_load_dwordx4 v[132:135], v206, s[28:29] offset:512
	global_load_dwordx2 v[42:43], v205, s[34:35] offset:288
	global_load_dwordx2 v[118:119], v204, s[30:31] offset:288
	global_load_dwordx4 v[136:139], v206, s[28:29] offset:576
	global_load_dwordx2 v[44:45], v205, s[34:35] offset:320
	global_load_dwordx2 v[120:121], v204, s[30:31] offset:320
	global_load_dwordx4 v[144:147], v206, s[28:29] offset:640
	global_load_dwordx2 v[46:47], v205, s[34:35] offset:352
	global_load_dwordx2 v[122:123], v204, s[30:31] offset:352
	global_load_dwordx4 v[148:151], v206, s[28:29] offset:704
	global_load_dwordx2 v[48:49], v205, s[34:35] offset:384
	global_load_dwordx2 v[124:125], v204, s[30:31] offset:384
	global_load_dwordx4 v[152:155], v206, s[28:29] offset:768
	global_load_dwordx2 v[50:51], v205, s[34:35] offset:416
	global_load_dwordx2 v[126:127], v204, s[30:31] offset:416
	global_load_dwordx4 v[156:159], v206, s[28:29] offset:832
	global_load_dwordx2 v[52:53], v205, s[34:35] offset:448
	global_load_dwordx2 v[128:129], v204, s[30:31] offset:448
	global_load_dwordx4 v[160:163], v206, s[28:29] offset:896
	global_load_dwordx2 v[54:55], v205, s[34:35] offset:480
	global_load_dwordx2 v[130:131], v204, s[30:31] offset:480
	global_load_dwordx4 v[164:167], v206, s[28:29] offset:960
	s_waitcnt vmcnt(45)
	v_lshlrev_b32_e32 v12, 16, v24
	v_and_b32_e32 v13, 0xffff0000, v24
	v_lshlrev_b32_e32 v14, 16, v25
	v_and_b32_e32 v15, 0xffff0000, v25
	v_mul_f32_e32 v16, 0xbfb8aa3b, v12
	v_mul_f32_e32 v17, 0xbfb8aa3b, v13
	v_mul_f32_e32 v18, 0xbfb8aa3b, v14
	v_mul_f32_e32 v19, 0xbfb8aa3b, v15
	v_exp_f32_e32 v16, v16
	v_exp_f32_e32 v17, v17
	v_exp_f32_e32 v18, v18
	v_exp_f32_e32 v19, v19
	v_lshlrev_b32_e32 v20, 16, v100
	v_and_b32_e32 v21, 0xffff0000, v100
	v_lshlrev_b32_e32 v22, 16, v101
	v_and_b32_e32 v23, 0xffff0000, v101
	v_add_f32_e32 v16, 1.0, v16
	v_add_f32_e32 v17, 1.0, v17
	v_add_f32_e32 v18, 1.0, v18
	v_add_f32_e32 v19, 1.0, v19
	v_rcp_f32_e32 v16, v16
	v_rcp_f32_e32 v17, v17
	v_rcp_f32_e32 v18, v18
	v_rcp_f32_e32 v19, v19
	v_sub_f32_e32 v20, v20, v227
	v_sub_f32_e32 v21, v21, v227
	v_sub_f32_e32 v22, v22, v227
	v_sub_f32_e32 v23, v23, v227
	v_mul_f32_e32 v20, v20, v228
	v_mul_f32_e32 v21, v21, v228
	v_mul_f32_e32 v22, v22, v228
	v_mul_f32_e32 v23, v23, v228
	v_mul_f32_e32 v12, v12, v16
	v_mul_f32_e32 v13, v13, v17
	v_mul_f32_e32 v14, v14, v18
	v_mul_f32_e32 v15, v15, v19
	v_mul_f32_e32 v20, v20, v68
	v_mul_f32_e32 v21, v21, v69
	v_mul_f32_e32 v22, v22, v70
	v_mul_f32_e32 v23, v23, v71
	v_mul_f32_e32 v20, v20, v12
	v_mul_f32_e32 v21, v21, v13
	v_mul_f32_e32 v22, v22, v14
	v_mul_f32_e32 v23, v23, v15
	v_cvt_pk_bf16_f32 v20, v20, v21
	v_cvt_pk_bf16_f32 v21, v22, v23
	global_store_dwordx2 v204, v[20:21], s[30:31] offset:0
	s_waitcnt vmcnt(43)
	v_lshlrev_b32_e32 v12, 16, v26
	v_and_b32_e32 v13, 0xffff0000, v26
	v_lshlrev_b32_e32 v14, 16, v27
	v_and_b32_e32 v15, 0xffff0000, v27
	v_mul_f32_e32 v16, 0xbfb8aa3b, v12
	v_mul_f32_e32 v17, 0xbfb8aa3b, v13
	v_mul_f32_e32 v18, 0xbfb8aa3b, v14
	v_mul_f32_e32 v19, 0xbfb8aa3b, v15
	v_exp_f32_e32 v16, v16
	v_exp_f32_e32 v17, v17
	v_exp_f32_e32 v18, v18
	v_exp_f32_e32 v19, v19
	v_lshlrev_b32_e32 v20, 16, v102
	v_and_b32_e32 v21, 0xffff0000, v102
	v_lshlrev_b32_e32 v22, 16, v103
	v_and_b32_e32 v23, 0xffff0000, v103
	v_add_f32_e32 v16, 1.0, v16
	v_add_f32_e32 v17, 1.0, v17
	v_add_f32_e32 v18, 1.0, v18
	v_add_f32_e32 v19, 1.0, v19
	v_rcp_f32_e32 v16, v16
	v_rcp_f32_e32 v17, v17
	v_rcp_f32_e32 v18, v18
	v_rcp_f32_e32 v19, v19
	v_sub_f32_e32 v20, v20, v227
	v_sub_f32_e32 v21, v21, v227
	v_sub_f32_e32 v22, v22, v227
	v_sub_f32_e32 v23, v23, v227
	v_mul_f32_e32 v20, v20, v228
	v_mul_f32_e32 v21, v21, v228
	v_mul_f32_e32 v22, v22, v228
	v_mul_f32_e32 v23, v23, v228
	v_mul_f32_e32 v12, v12, v16
	v_mul_f32_e32 v13, v13, v17
	v_mul_f32_e32 v14, v14, v18
	v_mul_f32_e32 v15, v15, v19
	v_mul_f32_e32 v20, v20, v72
	v_mul_f32_e32 v21, v21, v73
	v_mul_f32_e32 v22, v22, v74
	v_mul_f32_e32 v23, v23, v75
	v_mul_f32_e32 v20, v20, v12
	v_mul_f32_e32 v21, v21, v13
	v_mul_f32_e32 v22, v22, v14
	v_mul_f32_e32 v23, v23, v15
	v_cvt_pk_bf16_f32 v20, v20, v21
	v_cvt_pk_bf16_f32 v21, v22, v23
	global_store_dwordx2 v204, v[20:21], s[30:31] offset:32
	s_waitcnt vmcnt(41)
	v_lshlrev_b32_e32 v12, 16, v28
	v_and_b32_e32 v13, 0xffff0000, v28
	v_lshlrev_b32_e32 v14, 16, v29
	v_and_b32_e32 v15, 0xffff0000, v29
	v_mul_f32_e32 v16, 0xbfb8aa3b, v12
	v_mul_f32_e32 v17, 0xbfb8aa3b, v13
	v_mul_f32_e32 v18, 0xbfb8aa3b, v14
	v_mul_f32_e32 v19, 0xbfb8aa3b, v15
	v_exp_f32_e32 v16, v16
	v_exp_f32_e32 v17, v17
	v_exp_f32_e32 v18, v18
	v_exp_f32_e32 v19, v19
	v_lshlrev_b32_e32 v20, 16, v104
	v_and_b32_e32 v21, 0xffff0000, v104
	v_lshlrev_b32_e32 v22, 16, v105
	v_and_b32_e32 v23, 0xffff0000, v105
	v_add_f32_e32 v16, 1.0, v16
	v_add_f32_e32 v17, 1.0, v17
	v_add_f32_e32 v18, 1.0, v18
	v_add_f32_e32 v19, 1.0, v19
	v_rcp_f32_e32 v16, v16
	v_rcp_f32_e32 v17, v17
	v_rcp_f32_e32 v18, v18
	v_rcp_f32_e32 v19, v19
	v_sub_f32_e32 v20, v20, v227
	v_sub_f32_e32 v21, v21, v227
	v_sub_f32_e32 v22, v22, v227
	v_sub_f32_e32 v23, v23, v227
	v_mul_f32_e32 v20, v20, v228
	v_mul_f32_e32 v21, v21, v228
	v_mul_f32_e32 v22, v22, v228
	v_mul_f32_e32 v23, v23, v228
	v_mul_f32_e32 v12, v12, v16
	v_mul_f32_e32 v13, v13, v17
	v_mul_f32_e32 v14, v14, v18
	v_mul_f32_e32 v15, v15, v19
	v_mul_f32_e32 v20, v20, v76
	v_mul_f32_e32 v21, v21, v77
	v_mul_f32_e32 v22, v22, v78
	v_mul_f32_e32 v23, v23, v79
	v_mul_f32_e32 v20, v20, v12
	v_mul_f32_e32 v21, v21, v13
	v_mul_f32_e32 v22, v22, v14
	v_mul_f32_e32 v23, v23, v15
	v_cvt_pk_bf16_f32 v20, v20, v21
	v_cvt_pk_bf16_f32 v21, v22, v23
	global_store_dwordx2 v204, v[20:21], s[30:31] offset:64
	s_waitcnt vmcnt(39)
	v_lshlrev_b32_e32 v12, 16, v30
	v_and_b32_e32 v13, 0xffff0000, v30
	v_lshlrev_b32_e32 v14, 16, v31
	v_and_b32_e32 v15, 0xffff0000, v31
	v_mul_f32_e32 v16, 0xbfb8aa3b, v12
	v_mul_f32_e32 v17, 0xbfb8aa3b, v13
	v_mul_f32_e32 v18, 0xbfb8aa3b, v14
	v_mul_f32_e32 v19, 0xbfb8aa3b, v15
	v_exp_f32_e32 v16, v16
	v_exp_f32_e32 v17, v17
	v_exp_f32_e32 v18, v18
	v_exp_f32_e32 v19, v19
	v_lshlrev_b32_e32 v20, 16, v106
	v_and_b32_e32 v21, 0xffff0000, v106
	v_lshlrev_b32_e32 v22, 16, v107
	v_and_b32_e32 v23, 0xffff0000, v107
	v_add_f32_e32 v16, 1.0, v16
	v_add_f32_e32 v17, 1.0, v17
	v_add_f32_e32 v18, 1.0, v18
	v_add_f32_e32 v19, 1.0, v19
	v_rcp_f32_e32 v16, v16
	v_rcp_f32_e32 v17, v17
	v_rcp_f32_e32 v18, v18
	v_rcp_f32_e32 v19, v19
	v_sub_f32_e32 v20, v20, v227
	v_sub_f32_e32 v21, v21, v227
	v_sub_f32_e32 v22, v22, v227
	v_sub_f32_e32 v23, v23, v227
	v_mul_f32_e32 v20, v20, v228
	v_mul_f32_e32 v21, v21, v228
	v_mul_f32_e32 v22, v22, v228
	v_mul_f32_e32 v23, v23, v228
	v_mul_f32_e32 v12, v12, v16
	v_mul_f32_e32 v13, v13, v17
	v_mul_f32_e32 v14, v14, v18
	v_mul_f32_e32 v15, v15, v19
	v_mul_f32_e32 v20, v20, v80
	v_mul_f32_e32 v21, v21, v81
	v_mul_f32_e32 v22, v22, v82
	v_mul_f32_e32 v23, v23, v83
	v_mul_f32_e32 v20, v20, v12
	v_mul_f32_e32 v21, v21, v13
	v_mul_f32_e32 v22, v22, v14
	v_mul_f32_e32 v23, v23, v15
	v_cvt_pk_bf16_f32 v20, v20, v21
	v_cvt_pk_bf16_f32 v21, v22, v23
	global_store_dwordx2 v204, v[20:21], s[30:31] offset:96
	s_waitcnt vmcnt(37)
	v_lshlrev_b32_e32 v12, 16, v32
	v_and_b32_e32 v13, 0xffff0000, v32
	v_lshlrev_b32_e32 v14, 16, v33
	v_and_b32_e32 v15, 0xffff0000, v33
	v_mul_f32_e32 v16, 0xbfb8aa3b, v12
	v_mul_f32_e32 v17, 0xbfb8aa3b, v13
	v_mul_f32_e32 v18, 0xbfb8aa3b, v14
	v_mul_f32_e32 v19, 0xbfb8aa3b, v15
	v_exp_f32_e32 v16, v16
	v_exp_f32_e32 v17, v17
	v_exp_f32_e32 v18, v18
	v_exp_f32_e32 v19, v19
	v_lshlrev_b32_e32 v20, 16, v108
	v_and_b32_e32 v21, 0xffff0000, v108
	v_lshlrev_b32_e32 v22, 16, v109
	v_and_b32_e32 v23, 0xffff0000, v109
	v_add_f32_e32 v16, 1.0, v16
	v_add_f32_e32 v17, 1.0, v17
	v_add_f32_e32 v18, 1.0, v18
	v_add_f32_e32 v19, 1.0, v19
	v_rcp_f32_e32 v16, v16
	v_rcp_f32_e32 v17, v17
	v_rcp_f32_e32 v18, v18
	v_rcp_f32_e32 v19, v19
	v_sub_f32_e32 v20, v20, v227
	v_sub_f32_e32 v21, v21, v227
	v_sub_f32_e32 v22, v22, v227
	v_sub_f32_e32 v23, v23, v227
	v_mul_f32_e32 v20, v20, v228
	v_mul_f32_e32 v21, v21, v228
	v_mul_f32_e32 v22, v22, v228
	v_mul_f32_e32 v23, v23, v228
	v_mul_f32_e32 v12, v12, v16
	v_mul_f32_e32 v13, v13, v17
	v_mul_f32_e32 v14, v14, v18
	v_mul_f32_e32 v15, v15, v19
	v_mul_f32_e32 v20, v20, v84
	v_mul_f32_e32 v21, v21, v85
	v_mul_f32_e32 v22, v22, v86
	v_mul_f32_e32 v23, v23, v87
	v_mul_f32_e32 v20, v20, v12
	v_mul_f32_e32 v21, v21, v13
	v_mul_f32_e32 v22, v22, v14
	v_mul_f32_e32 v23, v23, v15
	v_cvt_pk_bf16_f32 v20, v20, v21
	v_cvt_pk_bf16_f32 v21, v22, v23
	global_store_dwordx2 v204, v[20:21], s[30:31] offset:128
	s_waitcnt vmcnt(35)
	v_lshlrev_b32_e32 v12, 16, v34
	v_and_b32_e32 v13, 0xffff0000, v34
	v_lshlrev_b32_e32 v14, 16, v35
	v_and_b32_e32 v15, 0xffff0000, v35
	v_mul_f32_e32 v16, 0xbfb8aa3b, v12
	v_mul_f32_e32 v17, 0xbfb8aa3b, v13
	v_mul_f32_e32 v18, 0xbfb8aa3b, v14
	v_mul_f32_e32 v19, 0xbfb8aa3b, v15
	v_exp_f32_e32 v16, v16
	v_exp_f32_e32 v17, v17
	v_exp_f32_e32 v18, v18
	v_exp_f32_e32 v19, v19
	v_lshlrev_b32_e32 v20, 16, v110
	v_and_b32_e32 v21, 0xffff0000, v110
	v_lshlrev_b32_e32 v22, 16, v111
	v_and_b32_e32 v23, 0xffff0000, v111
	v_add_f32_e32 v16, 1.0, v16
	v_add_f32_e32 v17, 1.0, v17
	v_add_f32_e32 v18, 1.0, v18
	v_add_f32_e32 v19, 1.0, v19
	v_rcp_f32_e32 v16, v16
	v_rcp_f32_e32 v17, v17
	v_rcp_f32_e32 v18, v18
	v_rcp_f32_e32 v19, v19
	v_sub_f32_e32 v20, v20, v227
	v_sub_f32_e32 v21, v21, v227
	v_sub_f32_e32 v22, v22, v227
	v_sub_f32_e32 v23, v23, v227
	v_mul_f32_e32 v20, v20, v228
	v_mul_f32_e32 v21, v21, v228
	v_mul_f32_e32 v22, v22, v228
	v_mul_f32_e32 v23, v23, v228
	v_mul_f32_e32 v12, v12, v16
	v_mul_f32_e32 v13, v13, v17
	v_mul_f32_e32 v14, v14, v18
	v_mul_f32_e32 v15, v15, v19
	v_mul_f32_e32 v20, v20, v88
	v_mul_f32_e32 v21, v21, v89
	v_mul_f32_e32 v22, v22, v90
	v_mul_f32_e32 v23, v23, v91
	v_mul_f32_e32 v20, v20, v12
	v_mul_f32_e32 v21, v21, v13
	v_mul_f32_e32 v22, v22, v14
	v_mul_f32_e32 v23, v23, v15
	v_cvt_pk_bf16_f32 v20, v20, v21
	v_cvt_pk_bf16_f32 v21, v22, v23
	global_store_dwordx2 v204, v[20:21], s[30:31] offset:160
	s_waitcnt vmcnt(33)
	v_lshlrev_b32_e32 v12, 16, v36
	v_and_b32_e32 v13, 0xffff0000, v36
	v_lshlrev_b32_e32 v14, 16, v37
	v_and_b32_e32 v15, 0xffff0000, v37
	v_mul_f32_e32 v16, 0xbfb8aa3b, v12
	v_mul_f32_e32 v17, 0xbfb8aa3b, v13
	v_mul_f32_e32 v18, 0xbfb8aa3b, v14
	v_mul_f32_e32 v19, 0xbfb8aa3b, v15
	v_exp_f32_e32 v16, v16
	v_exp_f32_e32 v17, v17
	v_exp_f32_e32 v18, v18
	v_exp_f32_e32 v19, v19
	v_lshlrev_b32_e32 v20, 16, v112
	v_and_b32_e32 v21, 0xffff0000, v112
	v_lshlrev_b32_e32 v22, 16, v113
	v_and_b32_e32 v23, 0xffff0000, v113
	v_add_f32_e32 v16, 1.0, v16
	v_add_f32_e32 v17, 1.0, v17
	v_add_f32_e32 v18, 1.0, v18
	v_add_f32_e32 v19, 1.0, v19
	v_rcp_f32_e32 v16, v16
	v_rcp_f32_e32 v17, v17
	v_rcp_f32_e32 v18, v18
	v_rcp_f32_e32 v19, v19
	v_sub_f32_e32 v20, v20, v227
	v_sub_f32_e32 v21, v21, v227
	v_sub_f32_e32 v22, v22, v227
	v_sub_f32_e32 v23, v23, v227
	v_mul_f32_e32 v20, v20, v228
	v_mul_f32_e32 v21, v21, v228
	v_mul_f32_e32 v22, v22, v228
	v_mul_f32_e32 v23, v23, v228
	v_mul_f32_e32 v12, v12, v16
	v_mul_f32_e32 v13, v13, v17
	v_mul_f32_e32 v14, v14, v18
	v_mul_f32_e32 v15, v15, v19
	v_mul_f32_e32 v20, v20, v92
	v_mul_f32_e32 v21, v21, v93
	v_mul_f32_e32 v22, v22, v94
	v_mul_f32_e32 v23, v23, v95
	v_mul_f32_e32 v20, v20, v12
	v_mul_f32_e32 v21, v21, v13
	v_mul_f32_e32 v22, v22, v14
	v_mul_f32_e32 v23, v23, v15
	v_cvt_pk_bf16_f32 v20, v20, v21
	v_cvt_pk_bf16_f32 v21, v22, v23
	global_store_dwordx2 v204, v[20:21], s[30:31] offset:192
	s_waitcnt vmcnt(31)
	v_lshlrev_b32_e32 v12, 16, v38
	v_and_b32_e32 v13, 0xffff0000, v38
	v_lshlrev_b32_e32 v14, 16, v39
	v_and_b32_e32 v15, 0xffff0000, v39
	v_mul_f32_e32 v16, 0xbfb8aa3b, v12
	v_mul_f32_e32 v17, 0xbfb8aa3b, v13
	v_mul_f32_e32 v18, 0xbfb8aa3b, v14
	v_mul_f32_e32 v19, 0xbfb8aa3b, v15
	v_exp_f32_e32 v16, v16
	v_exp_f32_e32 v17, v17
	v_exp_f32_e32 v18, v18
	v_exp_f32_e32 v19, v19
	v_lshlrev_b32_e32 v20, 16, v114
	v_and_b32_e32 v21, 0xffff0000, v114
	v_lshlrev_b32_e32 v22, 16, v115
	v_and_b32_e32 v23, 0xffff0000, v115
	v_add_f32_e32 v16, 1.0, v16
	v_add_f32_e32 v17, 1.0, v17
	v_add_f32_e32 v18, 1.0, v18
	v_add_f32_e32 v19, 1.0, v19
	v_rcp_f32_e32 v16, v16
	v_rcp_f32_e32 v17, v17
	v_rcp_f32_e32 v18, v18
	v_rcp_f32_e32 v19, v19
	v_sub_f32_e32 v20, v20, v227
	v_sub_f32_e32 v21, v21, v227
	v_sub_f32_e32 v22, v22, v227
	v_sub_f32_e32 v23, v23, v227
	v_mul_f32_e32 v20, v20, v228
	v_mul_f32_e32 v21, v21, v228
	v_mul_f32_e32 v22, v22, v228
	v_mul_f32_e32 v23, v23, v228
	v_mul_f32_e32 v12, v12, v16
	v_mul_f32_e32 v13, v13, v17
	v_mul_f32_e32 v14, v14, v18
	v_mul_f32_e32 v15, v15, v19
	v_mul_f32_e32 v20, v20, v96
	v_mul_f32_e32 v21, v21, v97
	v_mul_f32_e32 v22, v22, v98
	v_mul_f32_e32 v23, v23, v99
	v_mul_f32_e32 v20, v20, v12
	v_mul_f32_e32 v21, v21, v13
	v_mul_f32_e32 v22, v22, v14
	v_mul_f32_e32 v23, v23, v15
	v_cvt_pk_bf16_f32 v20, v20, v21
	v_cvt_pk_bf16_f32 v21, v22, v23
	global_store_dwordx2 v204, v[20:21], s[30:31] offset:224
	global_load_dwordx2 v[24:25], v205, s[34:35] offset:512
	global_load_dwordx2 v[100:101], v204, s[30:31] offset:512
	global_load_dwordx4 v[68:71], v206, s[28:29] offset:1024
	global_load_dwordx2 v[26:27], v205, s[34:35] offset:544
	global_load_dwordx2 v[102:103], v204, s[30:31] offset:544
	global_load_dwordx4 v[72:75], v206, s[28:29] offset:1088
	global_load_dwordx2 v[28:29], v205, s[34:35] offset:576
	global_load_dwordx2 v[104:105], v204, s[30:31] offset:576
	global_load_dwordx4 v[76:79], v206, s[28:29] offset:1152
	global_load_dwordx2 v[30:31], v205, s[34:35] offset:608
	global_load_dwordx2 v[106:107], v204, s[30:31] offset:608
	global_load_dwordx4 v[80:83], v206, s[28:29] offset:1216
	global_load_dwordx2 v[32:33], v205, s[34:35] offset:640
	global_load_dwordx2 v[108:109], v204, s[30:31] offset:640
	global_load_dwordx4 v[84:87], v206, s[28:29] offset:1280
	global_load_dwordx2 v[34:35], v205, s[34:35] offset:672
	global_load_dwordx2 v[110:111], v204, s[30:31] offset:672
	global_load_dwordx4 v[88:91], v206, s[28:29] offset:1344
	global_load_dwordx2 v[36:37], v205, s[34:35] offset:704
	global_load_dwordx2 v[112:113], v204, s[30:31] offset:704
	global_load_dwordx4 v[92:95], v206, s[28:29] offset:1408
	global_load_dwordx2 v[38:39], v205, s[34:35] offset:736
	global_load_dwordx2 v[114:115], v204, s[30:31] offset:736
	global_load_dwordx4 v[96:99], v206, s[28:29] offset:1472
	s_waitcnt vmcnt(53)
	v_lshlrev_b32_e32 v12, 16, v40
	v_and_b32_e32 v13, 0xffff0000, v40
	v_lshlrev_b32_e32 v14, 16, v41
	v_and_b32_e32 v15, 0xffff0000, v41
	v_mul_f32_e32 v16, 0xbfb8aa3b, v12
	v_mul_f32_e32 v17, 0xbfb8aa3b, v13
	v_mul_f32_e32 v18, 0xbfb8aa3b, v14
	v_mul_f32_e32 v19, 0xbfb8aa3b, v15
	v_exp_f32_e32 v16, v16
	v_exp_f32_e32 v17, v17
	v_exp_f32_e32 v18, v18
	v_exp_f32_e32 v19, v19
	v_lshlrev_b32_e32 v20, 16, v116
	v_and_b32_e32 v21, 0xffff0000, v116
	v_lshlrev_b32_e32 v22, 16, v117
	v_and_b32_e32 v23, 0xffff0000, v117
	v_add_f32_e32 v16, 1.0, v16
	v_add_f32_e32 v17, 1.0, v17
	v_add_f32_e32 v18, 1.0, v18
	v_add_f32_e32 v19, 1.0, v19
	v_rcp_f32_e32 v16, v16
	v_rcp_f32_e32 v17, v17
	v_rcp_f32_e32 v18, v18
	v_rcp_f32_e32 v19, v19
	v_sub_f32_e32 v20, v20, v227
	v_sub_f32_e32 v21, v21, v227
	v_sub_f32_e32 v22, v22, v227
	v_sub_f32_e32 v23, v23, v227
	v_mul_f32_e32 v20, v20, v228
	v_mul_f32_e32 v21, v21, v228
	v_mul_f32_e32 v22, v22, v228
	v_mul_f32_e32 v23, v23, v228
	v_mul_f32_e32 v12, v12, v16
	v_mul_f32_e32 v13, v13, v17
	v_mul_f32_e32 v14, v14, v18
	v_mul_f32_e32 v15, v15, v19
	v_mul_f32_e32 v20, v20, v132
	v_mul_f32_e32 v21, v21, v133
	v_mul_f32_e32 v22, v22, v134
	v_mul_f32_e32 v23, v23, v135
	v_mul_f32_e32 v20, v20, v12
	v_mul_f32_e32 v21, v21, v13
	v_mul_f32_e32 v22, v22, v14
	v_mul_f32_e32 v23, v23, v15
	v_cvt_pk_bf16_f32 v20, v20, v21
	v_cvt_pk_bf16_f32 v21, v22, v23
	global_store_dwordx2 v204, v[20:21], s[30:31] offset:256
	s_waitcnt vmcnt(51)
	v_lshlrev_b32_e32 v12, 16, v42
	v_and_b32_e32 v13, 0xffff0000, v42
	v_lshlrev_b32_e32 v14, 16, v43
	v_and_b32_e32 v15, 0xffff0000, v43
	v_mul_f32_e32 v16, 0xbfb8aa3b, v12
	v_mul_f32_e32 v17, 0xbfb8aa3b, v13
	v_mul_f32_e32 v18, 0xbfb8aa3b, v14
	v_mul_f32_e32 v19, 0xbfb8aa3b, v15
	v_exp_f32_e32 v16, v16
	v_exp_f32_e32 v17, v17
	v_exp_f32_e32 v18, v18
	v_exp_f32_e32 v19, v19
	v_lshlrev_b32_e32 v20, 16, v118
	v_and_b32_e32 v21, 0xffff0000, v118
	v_lshlrev_b32_e32 v22, 16, v119
	v_and_b32_e32 v23, 0xffff0000, v119
	v_add_f32_e32 v16, 1.0, v16
	v_add_f32_e32 v17, 1.0, v17
	v_add_f32_e32 v18, 1.0, v18
	v_add_f32_e32 v19, 1.0, v19
	v_rcp_f32_e32 v16, v16
	v_rcp_f32_e32 v17, v17
	v_rcp_f32_e32 v18, v18
	v_rcp_f32_e32 v19, v19
	v_sub_f32_e32 v20, v20, v227
	v_sub_f32_e32 v21, v21, v227
	v_sub_f32_e32 v22, v22, v227
	v_sub_f32_e32 v23, v23, v227
	v_mul_f32_e32 v20, v20, v228
	v_mul_f32_e32 v21, v21, v228
	v_mul_f32_e32 v22, v22, v228
	v_mul_f32_e32 v23, v23, v228
	v_mul_f32_e32 v12, v12, v16
	v_mul_f32_e32 v13, v13, v17
	v_mul_f32_e32 v14, v14, v18
	v_mul_f32_e32 v15, v15, v19
	v_mul_f32_e32 v20, v20, v136
	v_mul_f32_e32 v21, v21, v137
	v_mul_f32_e32 v22, v22, v138
	v_mul_f32_e32 v23, v23, v139
	v_mul_f32_e32 v20, v20, v12
	v_mul_f32_e32 v21, v21, v13
	v_mul_f32_e32 v22, v22, v14
	v_mul_f32_e32 v23, v23, v15
	v_cvt_pk_bf16_f32 v20, v20, v21
	v_cvt_pk_bf16_f32 v21, v22, v23
	global_store_dwordx2 v204, v[20:21], s[30:31] offset:288
	s_waitcnt vmcnt(49)
	v_lshlrev_b32_e32 v12, 16, v44
	v_and_b32_e32 v13, 0xffff0000, v44
	v_lshlrev_b32_e32 v14, 16, v45
	v_and_b32_e32 v15, 0xffff0000, v45
	v_mul_f32_e32 v16, 0xbfb8aa3b, v12
	v_mul_f32_e32 v17, 0xbfb8aa3b, v13
	v_mul_f32_e32 v18, 0xbfb8aa3b, v14
	v_mul_f32_e32 v19, 0xbfb8aa3b, v15
	v_exp_f32_e32 v16, v16
	v_exp_f32_e32 v17, v17
	v_exp_f32_e32 v18, v18
	v_exp_f32_e32 v19, v19
	v_lshlrev_b32_e32 v20, 16, v120
	v_and_b32_e32 v21, 0xffff0000, v120
	v_lshlrev_b32_e32 v22, 16, v121
	v_and_b32_e32 v23, 0xffff0000, v121
	v_add_f32_e32 v16, 1.0, v16
	v_add_f32_e32 v17, 1.0, v17
	v_add_f32_e32 v18, 1.0, v18
	v_add_f32_e32 v19, 1.0, v19
	v_rcp_f32_e32 v16, v16
	v_rcp_f32_e32 v17, v17
	v_rcp_f32_e32 v18, v18
	v_rcp_f32_e32 v19, v19
	v_sub_f32_e32 v20, v20, v227
	v_sub_f32_e32 v21, v21, v227
	v_sub_f32_e32 v22, v22, v227
	v_sub_f32_e32 v23, v23, v227
	v_mul_f32_e32 v20, v20, v228
	v_mul_f32_e32 v21, v21, v228
	v_mul_f32_e32 v22, v22, v228
	v_mul_f32_e32 v23, v23, v228
	v_mul_f32_e32 v12, v12, v16
	v_mul_f32_e32 v13, v13, v17
	v_mul_f32_e32 v14, v14, v18
	v_mul_f32_e32 v15, v15, v19
	v_mul_f32_e32 v20, v20, v144
	v_mul_f32_e32 v21, v21, v145
	v_mul_f32_e32 v22, v22, v146
	v_mul_f32_e32 v23, v23, v147
	v_mul_f32_e32 v20, v20, v12
	v_mul_f32_e32 v21, v21, v13
	v_mul_f32_e32 v22, v22, v14
	v_mul_f32_e32 v23, v23, v15
	v_cvt_pk_bf16_f32 v20, v20, v21
	v_cvt_pk_bf16_f32 v21, v22, v23
	global_store_dwordx2 v204, v[20:21], s[30:31] offset:320
	s_waitcnt vmcnt(47)
	v_lshlrev_b32_e32 v12, 16, v46
	v_and_b32_e32 v13, 0xffff0000, v46
	v_lshlrev_b32_e32 v14, 16, v47
	v_and_b32_e32 v15, 0xffff0000, v47
	v_mul_f32_e32 v16, 0xbfb8aa3b, v12
	v_mul_f32_e32 v17, 0xbfb8aa3b, v13
	v_mul_f32_e32 v18, 0xbfb8aa3b, v14
	v_mul_f32_e32 v19, 0xbfb8aa3b, v15
	v_exp_f32_e32 v16, v16
	v_exp_f32_e32 v17, v17
	v_exp_f32_e32 v18, v18
	v_exp_f32_e32 v19, v19
	v_lshlrev_b32_e32 v20, 16, v122
	v_and_b32_e32 v21, 0xffff0000, v122
	v_lshlrev_b32_e32 v22, 16, v123
	v_and_b32_e32 v23, 0xffff0000, v123
	v_add_f32_e32 v16, 1.0, v16
	v_add_f32_e32 v17, 1.0, v17
	v_add_f32_e32 v18, 1.0, v18
	v_add_f32_e32 v19, 1.0, v19
	v_rcp_f32_e32 v16, v16
	v_rcp_f32_e32 v17, v17
	v_rcp_f32_e32 v18, v18
	v_rcp_f32_e32 v19, v19
	v_sub_f32_e32 v20, v20, v227
	v_sub_f32_e32 v21, v21, v227
	v_sub_f32_e32 v22, v22, v227
	v_sub_f32_e32 v23, v23, v227
	v_mul_f32_e32 v20, v20, v228
	v_mul_f32_e32 v21, v21, v228
	v_mul_f32_e32 v22, v22, v228
	v_mul_f32_e32 v23, v23, v228
	v_mul_f32_e32 v12, v12, v16
	v_mul_f32_e32 v13, v13, v17
	v_mul_f32_e32 v14, v14, v18
	v_mul_f32_e32 v15, v15, v19
	v_mul_f32_e32 v20, v20, v148
	v_mul_f32_e32 v21, v21, v149
	v_mul_f32_e32 v22, v22, v150
	v_mul_f32_e32 v23, v23, v151
	v_mul_f32_e32 v20, v20, v12
	v_mul_f32_e32 v21, v21, v13
	v_mul_f32_e32 v22, v22, v14
	v_mul_f32_e32 v23, v23, v15
	v_cvt_pk_bf16_f32 v20, v20, v21
	v_cvt_pk_bf16_f32 v21, v22, v23
	global_store_dwordx2 v204, v[20:21], s[30:31] offset:352
	s_waitcnt vmcnt(45)
	v_lshlrev_b32_e32 v12, 16, v48
	v_and_b32_e32 v13, 0xffff0000, v48
	v_lshlrev_b32_e32 v14, 16, v49
	v_and_b32_e32 v15, 0xffff0000, v49
	v_mul_f32_e32 v16, 0xbfb8aa3b, v12
	v_mul_f32_e32 v17, 0xbfb8aa3b, v13
	v_mul_f32_e32 v18, 0xbfb8aa3b, v14
	v_mul_f32_e32 v19, 0xbfb8aa3b, v15
	v_exp_f32_e32 v16, v16
	v_exp_f32_e32 v17, v17
	v_exp_f32_e32 v18, v18
	v_exp_f32_e32 v19, v19
	v_lshlrev_b32_e32 v20, 16, v124
	v_and_b32_e32 v21, 0xffff0000, v124
	v_lshlrev_b32_e32 v22, 16, v125
	v_and_b32_e32 v23, 0xffff0000, v125
	v_add_f32_e32 v16, 1.0, v16
	v_add_f32_e32 v17, 1.0, v17
	v_add_f32_e32 v18, 1.0, v18
	v_add_f32_e32 v19, 1.0, v19
	v_rcp_f32_e32 v16, v16
	v_rcp_f32_e32 v17, v17
	v_rcp_f32_e32 v18, v18
	v_rcp_f32_e32 v19, v19
	v_sub_f32_e32 v20, v20, v227
	v_sub_f32_e32 v21, v21, v227
	v_sub_f32_e32 v22, v22, v227
	v_sub_f32_e32 v23, v23, v227
	v_mul_f32_e32 v20, v20, v228
	v_mul_f32_e32 v21, v21, v228
	v_mul_f32_e32 v22, v22, v228
	v_mul_f32_e32 v23, v23, v228
	v_mul_f32_e32 v12, v12, v16
	v_mul_f32_e32 v13, v13, v17
	v_mul_f32_e32 v14, v14, v18
	v_mul_f32_e32 v15, v15, v19
	v_mul_f32_e32 v20, v20, v152
	v_mul_f32_e32 v21, v21, v153
	v_mul_f32_e32 v22, v22, v154
	v_mul_f32_e32 v23, v23, v155
	v_mul_f32_e32 v20, v20, v12
	v_mul_f32_e32 v21, v21, v13
	v_mul_f32_e32 v22, v22, v14
	v_mul_f32_e32 v23, v23, v15
	v_cvt_pk_bf16_f32 v20, v20, v21
	v_cvt_pk_bf16_f32 v21, v22, v23
	global_store_dwordx2 v204, v[20:21], s[30:31] offset:384
	s_waitcnt vmcnt(43)
	v_lshlrev_b32_e32 v12, 16, v50
	v_and_b32_e32 v13, 0xffff0000, v50
	v_lshlrev_b32_e32 v14, 16, v51
	v_and_b32_e32 v15, 0xffff0000, v51
	v_mul_f32_e32 v16, 0xbfb8aa3b, v12
	v_mul_f32_e32 v17, 0xbfb8aa3b, v13
	v_mul_f32_e32 v18, 0xbfb8aa3b, v14
	v_mul_f32_e32 v19, 0xbfb8aa3b, v15
	v_exp_f32_e32 v16, v16
	v_exp_f32_e32 v17, v17
	v_exp_f32_e32 v18, v18
	v_exp_f32_e32 v19, v19
	v_lshlrev_b32_e32 v20, 16, v126
	v_and_b32_e32 v21, 0xffff0000, v126
	v_lshlrev_b32_e32 v22, 16, v127
	v_and_b32_e32 v23, 0xffff0000, v127
	v_add_f32_e32 v16, 1.0, v16
	v_add_f32_e32 v17, 1.0, v17
	v_add_f32_e32 v18, 1.0, v18
	v_add_f32_e32 v19, 1.0, v19
	v_rcp_f32_e32 v16, v16
	v_rcp_f32_e32 v17, v17
	v_rcp_f32_e32 v18, v18
	v_rcp_f32_e32 v19, v19
	v_sub_f32_e32 v20, v20, v227
	v_sub_f32_e32 v21, v21, v227
	v_sub_f32_e32 v22, v22, v227
	v_sub_f32_e32 v23, v23, v227
	v_mul_f32_e32 v20, v20, v228
	v_mul_f32_e32 v21, v21, v228
	v_mul_f32_e32 v22, v22, v228
	v_mul_f32_e32 v23, v23, v228
	v_mul_f32_e32 v12, v12, v16
	v_mul_f32_e32 v13, v13, v17
	v_mul_f32_e32 v14, v14, v18
	v_mul_f32_e32 v15, v15, v19
	v_mul_f32_e32 v20, v20, v156
	v_mul_f32_e32 v21, v21, v157
	v_mul_f32_e32 v22, v22, v158
	v_mul_f32_e32 v23, v23, v159
	v_mul_f32_e32 v20, v20, v12
	v_mul_f32_e32 v21, v21, v13
	v_mul_f32_e32 v22, v22, v14
	v_mul_f32_e32 v23, v23, v15
	v_cvt_pk_bf16_f32 v20, v20, v21
	v_cvt_pk_bf16_f32 v21, v22, v23
	global_store_dwordx2 v204, v[20:21], s[30:31] offset:416
	s_waitcnt vmcnt(41)
	v_lshlrev_b32_e32 v12, 16, v52
	v_and_b32_e32 v13, 0xffff0000, v52
	v_lshlrev_b32_e32 v14, 16, v53
	v_and_b32_e32 v15, 0xffff0000, v53
	v_mul_f32_e32 v16, 0xbfb8aa3b, v12
	v_mul_f32_e32 v17, 0xbfb8aa3b, v13
	v_mul_f32_e32 v18, 0xbfb8aa3b, v14
	v_mul_f32_e32 v19, 0xbfb8aa3b, v15
	v_exp_f32_e32 v16, v16
	v_exp_f32_e32 v17, v17
	v_exp_f32_e32 v18, v18
	v_exp_f32_e32 v19, v19
	v_lshlrev_b32_e32 v20, 16, v128
	v_and_b32_e32 v21, 0xffff0000, v128
	v_lshlrev_b32_e32 v22, 16, v129
	v_and_b32_e32 v23, 0xffff0000, v129
	v_add_f32_e32 v16, 1.0, v16
	v_add_f32_e32 v17, 1.0, v17
	v_add_f32_e32 v18, 1.0, v18
	v_add_f32_e32 v19, 1.0, v19
	v_rcp_f32_e32 v16, v16
	v_rcp_f32_e32 v17, v17
	v_rcp_f32_e32 v18, v18
	v_rcp_f32_e32 v19, v19
	v_sub_f32_e32 v20, v20, v227
	v_sub_f32_e32 v21, v21, v227
	v_sub_f32_e32 v22, v22, v227
	v_sub_f32_e32 v23, v23, v227
	v_mul_f32_e32 v20, v20, v228
	v_mul_f32_e32 v21, v21, v228
	v_mul_f32_e32 v22, v22, v228
	v_mul_f32_e32 v23, v23, v228
	v_mul_f32_e32 v12, v12, v16
	v_mul_f32_e32 v13, v13, v17
	v_mul_f32_e32 v14, v14, v18
	v_mul_f32_e32 v15, v15, v19
	v_mul_f32_e32 v20, v20, v160
	v_mul_f32_e32 v21, v21, v161
	v_mul_f32_e32 v22, v22, v162
	v_mul_f32_e32 v23, v23, v163
	v_mul_f32_e32 v20, v20, v12
	v_mul_f32_e32 v21, v21, v13
	v_mul_f32_e32 v22, v22, v14
	v_mul_f32_e32 v23, v23, v15
	v_cvt_pk_bf16_f32 v20, v20, v21
	v_cvt_pk_bf16_f32 v21, v22, v23
	global_store_dwordx2 v204, v[20:21], s[30:31] offset:448
	s_waitcnt vmcnt(39)
	v_lshlrev_b32_e32 v12, 16, v54
	v_and_b32_e32 v13, 0xffff0000, v54
	v_lshlrev_b32_e32 v14, 16, v55
	v_and_b32_e32 v15, 0xffff0000, v55
	v_mul_f32_e32 v16, 0xbfb8aa3b, v12
	v_mul_f32_e32 v17, 0xbfb8aa3b, v13
	v_mul_f32_e32 v18, 0xbfb8aa3b, v14
	v_mul_f32_e32 v19, 0xbfb8aa3b, v15
	v_exp_f32_e32 v16, v16
	v_exp_f32_e32 v17, v17
	v_exp_f32_e32 v18, v18
	v_exp_f32_e32 v19, v19
	v_lshlrev_b32_e32 v20, 16, v130
	v_and_b32_e32 v21, 0xffff0000, v130
	v_lshlrev_b32_e32 v22, 16, v131
	v_and_b32_e32 v23, 0xffff0000, v131
	v_add_f32_e32 v16, 1.0, v16
	v_add_f32_e32 v17, 1.0, v17
	v_add_f32_e32 v18, 1.0, v18
	v_add_f32_e32 v19, 1.0, v19
	v_rcp_f32_e32 v16, v16
	v_rcp_f32_e32 v17, v17
	v_rcp_f32_e32 v18, v18
	v_rcp_f32_e32 v19, v19
	v_sub_f32_e32 v20, v20, v227
	v_sub_f32_e32 v21, v21, v227
	v_sub_f32_e32 v22, v22, v227
	v_sub_f32_e32 v23, v23, v227
	v_mul_f32_e32 v20, v20, v228
	v_mul_f32_e32 v21, v21, v228
	v_mul_f32_e32 v22, v22, v228
	v_mul_f32_e32 v23, v23, v228
	v_mul_f32_e32 v12, v12, v16
	v_mul_f32_e32 v13, v13, v17
	v_mul_f32_e32 v14, v14, v18
	v_mul_f32_e32 v15, v15, v19
	v_mul_f32_e32 v20, v20, v164
	v_mul_f32_e32 v21, v21, v165
	v_mul_f32_e32 v22, v22, v166
	v_mul_f32_e32 v23, v23, v167
	v_mul_f32_e32 v20, v20, v12
	v_mul_f32_e32 v21, v21, v13
	v_mul_f32_e32 v22, v22, v14
	v_mul_f32_e32 v23, v23, v15
	v_cvt_pk_bf16_f32 v20, v20, v21
	v_cvt_pk_bf16_f32 v21, v22, v23
	global_store_dwordx2 v204, v[20:21], s[30:31] offset:480
	global_load_dwordx2 v[40:41], v205, s[34:35] offset:768
	global_load_dwordx2 v[116:117], v204, s[30:31] offset:768
	global_load_dwordx4 v[132:135], v206, s[28:29] offset:1536
	global_load_dwordx2 v[42:43], v205, s[34:35] offset:800
	global_load_dwordx2 v[118:119], v204, s[30:31] offset:800
	global_load_dwordx4 v[136:139], v206, s[28:29] offset:1600
	global_load_dwordx2 v[44:45], v205, s[34:35] offset:832
	global_load_dwordx2 v[120:121], v204, s[30:31] offset:832
	global_load_dwordx4 v[144:147], v206, s[28:29] offset:1664
	global_load_dwordx2 v[46:47], v205, s[34:35] offset:864
	global_load_dwordx2 v[122:123], v204, s[30:31] offset:864
	global_load_dwordx4 v[148:151], v206, s[28:29] offset:1728
	global_load_dwordx2 v[48:49], v205, s[34:35] offset:896
	global_load_dwordx2 v[124:125], v204, s[30:31] offset:896
	global_load_dwordx4 v[152:155], v206, s[28:29] offset:1792
	global_load_dwordx2 v[50:51], v205, s[34:35] offset:928
	global_load_dwordx2 v[126:127], v204, s[30:31] offset:928
	global_load_dwordx4 v[156:159], v206, s[28:29] offset:1856
	global_load_dwordx2 v[52:53], v205, s[34:35] offset:960
	global_load_dwordx2 v[128:129], v204, s[30:31] offset:960
	global_load_dwordx4 v[160:163], v206, s[28:29] offset:1920
	global_load_dwordx2 v[54:55], v205, s[34:35] offset:992
	global_load_dwordx2 v[130:131], v204, s[30:31] offset:992
	global_load_dwordx4 v[164:167], v206, s[28:29] offset:1984
	s_waitcnt vmcnt(53)
	v_lshlrev_b32_e32 v12, 16, v24
	v_and_b32_e32 v13, 0xffff0000, v24
	v_lshlrev_b32_e32 v14, 16, v25
	v_and_b32_e32 v15, 0xffff0000, v25
	v_mul_f32_e32 v16, 0xbfb8aa3b, v12
	v_mul_f32_e32 v17, 0xbfb8aa3b, v13
	v_mul_f32_e32 v18, 0xbfb8aa3b, v14
	v_mul_f32_e32 v19, 0xbfb8aa3b, v15
	v_exp_f32_e32 v16, v16
	v_exp_f32_e32 v17, v17
	v_exp_f32_e32 v18, v18
	v_exp_f32_e32 v19, v19
	v_lshlrev_b32_e32 v20, 16, v100
	v_and_b32_e32 v21, 0xffff0000, v100
	v_lshlrev_b32_e32 v22, 16, v101
	v_and_b32_e32 v23, 0xffff0000, v101
	v_add_f32_e32 v16, 1.0, v16
	v_add_f32_e32 v17, 1.0, v17
	v_add_f32_e32 v18, 1.0, v18
	v_add_f32_e32 v19, 1.0, v19
	v_rcp_f32_e32 v16, v16
	v_rcp_f32_e32 v17, v17
	v_rcp_f32_e32 v18, v18
	v_rcp_f32_e32 v19, v19
	v_sub_f32_e32 v20, v20, v227
	v_sub_f32_e32 v21, v21, v227
	v_sub_f32_e32 v22, v22, v227
	v_sub_f32_e32 v23, v23, v227
	v_mul_f32_e32 v20, v20, v228
	v_mul_f32_e32 v21, v21, v228
	v_mul_f32_e32 v22, v22, v228
	v_mul_f32_e32 v23, v23, v228
	v_mul_f32_e32 v12, v12, v16
	v_mul_f32_e32 v13, v13, v17
	v_mul_f32_e32 v14, v14, v18
	v_mul_f32_e32 v15, v15, v19
	v_mul_f32_e32 v20, v20, v68
	v_mul_f32_e32 v21, v21, v69
	v_mul_f32_e32 v22, v22, v70
	v_mul_f32_e32 v23, v23, v71
	v_mul_f32_e32 v20, v20, v12
	v_mul_f32_e32 v21, v21, v13
	v_mul_f32_e32 v22, v22, v14
	v_mul_f32_e32 v23, v23, v15
	v_cvt_pk_bf16_f32 v20, v20, v21
	v_cvt_pk_bf16_f32 v21, v22, v23
	global_store_dwordx2 v204, v[20:21], s[30:31] offset:512
	s_waitcnt vmcnt(51)
	v_lshlrev_b32_e32 v12, 16, v26
	v_and_b32_e32 v13, 0xffff0000, v26
	v_lshlrev_b32_e32 v14, 16, v27
	v_and_b32_e32 v15, 0xffff0000, v27
	v_mul_f32_e32 v16, 0xbfb8aa3b, v12
	v_mul_f32_e32 v17, 0xbfb8aa3b, v13
	v_mul_f32_e32 v18, 0xbfb8aa3b, v14
	v_mul_f32_e32 v19, 0xbfb8aa3b, v15
	v_exp_f32_e32 v16, v16
	v_exp_f32_e32 v17, v17
	v_exp_f32_e32 v18, v18
	v_exp_f32_e32 v19, v19
	v_lshlrev_b32_e32 v20, 16, v102
	v_and_b32_e32 v21, 0xffff0000, v102
	v_lshlrev_b32_e32 v22, 16, v103
	v_and_b32_e32 v23, 0xffff0000, v103
	v_add_f32_e32 v16, 1.0, v16
	v_add_f32_e32 v17, 1.0, v17
	v_add_f32_e32 v18, 1.0, v18
	v_add_f32_e32 v19, 1.0, v19
	v_rcp_f32_e32 v16, v16
	v_rcp_f32_e32 v17, v17
	v_rcp_f32_e32 v18, v18
	v_rcp_f32_e32 v19, v19
	v_sub_f32_e32 v20, v20, v227
	v_sub_f32_e32 v21, v21, v227
	v_sub_f32_e32 v22, v22, v227
	v_sub_f32_e32 v23, v23, v227
	v_mul_f32_e32 v20, v20, v228
	v_mul_f32_e32 v21, v21, v228
	v_mul_f32_e32 v22, v22, v228
	v_mul_f32_e32 v23, v23, v228
	v_mul_f32_e32 v12, v12, v16
	v_mul_f32_e32 v13, v13, v17
	v_mul_f32_e32 v14, v14, v18
	v_mul_f32_e32 v15, v15, v19
	v_mul_f32_e32 v20, v20, v72
	v_mul_f32_e32 v21, v21, v73
	v_mul_f32_e32 v22, v22, v74
	v_mul_f32_e32 v23, v23, v75
	v_mul_f32_e32 v20, v20, v12
	v_mul_f32_e32 v21, v21, v13
	v_mul_f32_e32 v22, v22, v14
	v_mul_f32_e32 v23, v23, v15
	v_cvt_pk_bf16_f32 v20, v20, v21
	v_cvt_pk_bf16_f32 v21, v22, v23
	global_store_dwordx2 v204, v[20:21], s[30:31] offset:544
	s_waitcnt vmcnt(49)
	v_lshlrev_b32_e32 v12, 16, v28
	v_and_b32_e32 v13, 0xffff0000, v28
	v_lshlrev_b32_e32 v14, 16, v29
	v_and_b32_e32 v15, 0xffff0000, v29
	v_mul_f32_e32 v16, 0xbfb8aa3b, v12
	v_mul_f32_e32 v17, 0xbfb8aa3b, v13
	v_mul_f32_e32 v18, 0xbfb8aa3b, v14
	v_mul_f32_e32 v19, 0xbfb8aa3b, v15
	v_exp_f32_e32 v16, v16
	v_exp_f32_e32 v17, v17
	v_exp_f32_e32 v18, v18
	v_exp_f32_e32 v19, v19
	v_lshlrev_b32_e32 v20, 16, v104
	v_and_b32_e32 v21, 0xffff0000, v104
	v_lshlrev_b32_e32 v22, 16, v105
	v_and_b32_e32 v23, 0xffff0000, v105
	v_add_f32_e32 v16, 1.0, v16
	v_add_f32_e32 v17, 1.0, v17
	v_add_f32_e32 v18, 1.0, v18
	v_add_f32_e32 v19, 1.0, v19
	v_rcp_f32_e32 v16, v16
	v_rcp_f32_e32 v17, v17
	v_rcp_f32_e32 v18, v18
	v_rcp_f32_e32 v19, v19
	v_sub_f32_e32 v20, v20, v227
	v_sub_f32_e32 v21, v21, v227
	v_sub_f32_e32 v22, v22, v227
	v_sub_f32_e32 v23, v23, v227
	v_mul_f32_e32 v20, v20, v228
	v_mul_f32_e32 v21, v21, v228
	v_mul_f32_e32 v22, v22, v228
	v_mul_f32_e32 v23, v23, v228
	v_mul_f32_e32 v12, v12, v16
	v_mul_f32_e32 v13, v13, v17
	v_mul_f32_e32 v14, v14, v18
	v_mul_f32_e32 v15, v15, v19
	v_mul_f32_e32 v20, v20, v76
	v_mul_f32_e32 v21, v21, v77
	v_mul_f32_e32 v22, v22, v78
	v_mul_f32_e32 v23, v23, v79
	v_mul_f32_e32 v20, v20, v12
	v_mul_f32_e32 v21, v21, v13
	v_mul_f32_e32 v22, v22, v14
	v_mul_f32_e32 v23, v23, v15
	v_cvt_pk_bf16_f32 v20, v20, v21
	v_cvt_pk_bf16_f32 v21, v22, v23
	global_store_dwordx2 v204, v[20:21], s[30:31] offset:576
	s_waitcnt vmcnt(47)
	v_lshlrev_b32_e32 v12, 16, v30
	v_and_b32_e32 v13, 0xffff0000, v30
	v_lshlrev_b32_e32 v14, 16, v31
	v_and_b32_e32 v15, 0xffff0000, v31
	v_mul_f32_e32 v16, 0xbfb8aa3b, v12
	v_mul_f32_e32 v17, 0xbfb8aa3b, v13
	v_mul_f32_e32 v18, 0xbfb8aa3b, v14
	v_mul_f32_e32 v19, 0xbfb8aa3b, v15
	v_exp_f32_e32 v16, v16
	v_exp_f32_e32 v17, v17
	v_exp_f32_e32 v18, v18
	v_exp_f32_e32 v19, v19
	v_lshlrev_b32_e32 v20, 16, v106
	v_and_b32_e32 v21, 0xffff0000, v106
	v_lshlrev_b32_e32 v22, 16, v107
	v_and_b32_e32 v23, 0xffff0000, v107
	v_add_f32_e32 v16, 1.0, v16
	v_add_f32_e32 v17, 1.0, v17
	v_add_f32_e32 v18, 1.0, v18
	v_add_f32_e32 v19, 1.0, v19
	v_rcp_f32_e32 v16, v16
	v_rcp_f32_e32 v17, v17
	v_rcp_f32_e32 v18, v18
	v_rcp_f32_e32 v19, v19
	v_sub_f32_e32 v20, v20, v227
	v_sub_f32_e32 v21, v21, v227
	v_sub_f32_e32 v22, v22, v227
	v_sub_f32_e32 v23, v23, v227
	v_mul_f32_e32 v20, v20, v228
	v_mul_f32_e32 v21, v21, v228
	v_mul_f32_e32 v22, v22, v228
	v_mul_f32_e32 v23, v23, v228
	v_mul_f32_e32 v12, v12, v16
	v_mul_f32_e32 v13, v13, v17
	v_mul_f32_e32 v14, v14, v18
	v_mul_f32_e32 v15, v15, v19
	v_mul_f32_e32 v20, v20, v80
	v_mul_f32_e32 v21, v21, v81
	v_mul_f32_e32 v22, v22, v82
	v_mul_f32_e32 v23, v23, v83
	v_mul_f32_e32 v20, v20, v12
	v_mul_f32_e32 v21, v21, v13
	v_mul_f32_e32 v22, v22, v14
	v_mul_f32_e32 v23, v23, v15
	v_cvt_pk_bf16_f32 v20, v20, v21
	v_cvt_pk_bf16_f32 v21, v22, v23
	global_store_dwordx2 v204, v[20:21], s[30:31] offset:608
	s_waitcnt vmcnt(45)
	v_lshlrev_b32_e32 v12, 16, v32
	v_and_b32_e32 v13, 0xffff0000, v32
	v_lshlrev_b32_e32 v14, 16, v33
	v_and_b32_e32 v15, 0xffff0000, v33
	v_mul_f32_e32 v16, 0xbfb8aa3b, v12
	v_mul_f32_e32 v17, 0xbfb8aa3b, v13
	v_mul_f32_e32 v18, 0xbfb8aa3b, v14
	v_mul_f32_e32 v19, 0xbfb8aa3b, v15
	v_exp_f32_e32 v16, v16
	v_exp_f32_e32 v17, v17
	v_exp_f32_e32 v18, v18
	v_exp_f32_e32 v19, v19
	v_lshlrev_b32_e32 v20, 16, v108
	v_and_b32_e32 v21, 0xffff0000, v108
	v_lshlrev_b32_e32 v22, 16, v109
	v_and_b32_e32 v23, 0xffff0000, v109
	v_add_f32_e32 v16, 1.0, v16
	v_add_f32_e32 v17, 1.0, v17
	v_add_f32_e32 v18, 1.0, v18
	v_add_f32_e32 v19, 1.0, v19
	v_rcp_f32_e32 v16, v16
	v_rcp_f32_e32 v17, v17
	v_rcp_f32_e32 v18, v18
	v_rcp_f32_e32 v19, v19
	v_sub_f32_e32 v20, v20, v227
	v_sub_f32_e32 v21, v21, v227
	v_sub_f32_e32 v22, v22, v227
	v_sub_f32_e32 v23, v23, v227
	v_mul_f32_e32 v20, v20, v228
	v_mul_f32_e32 v21, v21, v228
	v_mul_f32_e32 v22, v22, v228
	v_mul_f32_e32 v23, v23, v228
	v_mul_f32_e32 v12, v12, v16
	v_mul_f32_e32 v13, v13, v17
	v_mul_f32_e32 v14, v14, v18
	v_mul_f32_e32 v15, v15, v19
	v_mul_f32_e32 v20, v20, v84
	v_mul_f32_e32 v21, v21, v85
	v_mul_f32_e32 v22, v22, v86
	v_mul_f32_e32 v23, v23, v87
	v_mul_f32_e32 v20, v20, v12
	v_mul_f32_e32 v21, v21, v13
	v_mul_f32_e32 v22, v22, v14
	v_mul_f32_e32 v23, v23, v15
	v_cvt_pk_bf16_f32 v20, v20, v21
	v_cvt_pk_bf16_f32 v21, v22, v23
	global_store_dwordx2 v204, v[20:21], s[30:31] offset:640
	s_waitcnt vmcnt(43)
	v_lshlrev_b32_e32 v12, 16, v34
	v_and_b32_e32 v13, 0xffff0000, v34
	v_lshlrev_b32_e32 v14, 16, v35
	v_and_b32_e32 v15, 0xffff0000, v35
	v_mul_f32_e32 v16, 0xbfb8aa3b, v12
	v_mul_f32_e32 v17, 0xbfb8aa3b, v13
	v_mul_f32_e32 v18, 0xbfb8aa3b, v14
	v_mul_f32_e32 v19, 0xbfb8aa3b, v15
	v_exp_f32_e32 v16, v16
	v_exp_f32_e32 v17, v17
	v_exp_f32_e32 v18, v18
	v_exp_f32_e32 v19, v19
	v_lshlrev_b32_e32 v20, 16, v110
	v_and_b32_e32 v21, 0xffff0000, v110
	v_lshlrev_b32_e32 v22, 16, v111
	v_and_b32_e32 v23, 0xffff0000, v111
	v_add_f32_e32 v16, 1.0, v16
	v_add_f32_e32 v17, 1.0, v17
	v_add_f32_e32 v18, 1.0, v18
	v_add_f32_e32 v19, 1.0, v19
	v_rcp_f32_e32 v16, v16
	v_rcp_f32_e32 v17, v17
	v_rcp_f32_e32 v18, v18
	v_rcp_f32_e32 v19, v19
	v_sub_f32_e32 v20, v20, v227
	v_sub_f32_e32 v21, v21, v227
	v_sub_f32_e32 v22, v22, v227
	v_sub_f32_e32 v23, v23, v227
	v_mul_f32_e32 v20, v20, v228
	v_mul_f32_e32 v21, v21, v228
	v_mul_f32_e32 v22, v22, v228
	v_mul_f32_e32 v23, v23, v228
	v_mul_f32_e32 v12, v12, v16
	v_mul_f32_e32 v13, v13, v17
	v_mul_f32_e32 v14, v14, v18
	v_mul_f32_e32 v15, v15, v19
	v_mul_f32_e32 v20, v20, v88
	v_mul_f32_e32 v21, v21, v89
	v_mul_f32_e32 v22, v22, v90
	v_mul_f32_e32 v23, v23, v91
	v_mul_f32_e32 v20, v20, v12
	v_mul_f32_e32 v21, v21, v13
	v_mul_f32_e32 v22, v22, v14
	v_mul_f32_e32 v23, v23, v15
	v_cvt_pk_bf16_f32 v20, v20, v21
	v_cvt_pk_bf16_f32 v21, v22, v23
	global_store_dwordx2 v204, v[20:21], s[30:31] offset:672
	s_waitcnt vmcnt(41)
	v_lshlrev_b32_e32 v12, 16, v36
	v_and_b32_e32 v13, 0xffff0000, v36
	v_lshlrev_b32_e32 v14, 16, v37
	v_and_b32_e32 v15, 0xffff0000, v37
	v_mul_f32_e32 v16, 0xbfb8aa3b, v12
	v_mul_f32_e32 v17, 0xbfb8aa3b, v13
	v_mul_f32_e32 v18, 0xbfb8aa3b, v14
	v_mul_f32_e32 v19, 0xbfb8aa3b, v15
	v_exp_f32_e32 v16, v16
	v_exp_f32_e32 v17, v17
	v_exp_f32_e32 v18, v18
	v_exp_f32_e32 v19, v19
	v_lshlrev_b32_e32 v20, 16, v112
	v_and_b32_e32 v21, 0xffff0000, v112
	v_lshlrev_b32_e32 v22, 16, v113
	v_and_b32_e32 v23, 0xffff0000, v113
	v_add_f32_e32 v16, 1.0, v16
	v_add_f32_e32 v17, 1.0, v17
	v_add_f32_e32 v18, 1.0, v18
	v_add_f32_e32 v19, 1.0, v19
	v_rcp_f32_e32 v16, v16
	v_rcp_f32_e32 v17, v17
	v_rcp_f32_e32 v18, v18
	v_rcp_f32_e32 v19, v19
	v_sub_f32_e32 v20, v20, v227
	v_sub_f32_e32 v21, v21, v227
	v_sub_f32_e32 v22, v22, v227
	v_sub_f32_e32 v23, v23, v227
	v_mul_f32_e32 v20, v20, v228
	v_mul_f32_e32 v21, v21, v228
	v_mul_f32_e32 v22, v22, v228
	v_mul_f32_e32 v23, v23, v228
	v_mul_f32_e32 v12, v12, v16
	v_mul_f32_e32 v13, v13, v17
	v_mul_f32_e32 v14, v14, v18
	v_mul_f32_e32 v15, v15, v19
	v_mul_f32_e32 v20, v20, v92
	v_mul_f32_e32 v21, v21, v93
	v_mul_f32_e32 v22, v22, v94
	v_mul_f32_e32 v23, v23, v95
	v_mul_f32_e32 v20, v20, v12
	v_mul_f32_e32 v21, v21, v13
	v_mul_f32_e32 v22, v22, v14
	v_mul_f32_e32 v23, v23, v15
	v_cvt_pk_bf16_f32 v20, v20, v21
	v_cvt_pk_bf16_f32 v21, v22, v23
	global_store_dwordx2 v204, v[20:21], s[30:31] offset:704
	s_waitcnt vmcnt(39)
	v_lshlrev_b32_e32 v12, 16, v38
	v_and_b32_e32 v13, 0xffff0000, v38
	v_lshlrev_b32_e32 v14, 16, v39
	v_and_b32_e32 v15, 0xffff0000, v39
	v_mul_f32_e32 v16, 0xbfb8aa3b, v12
	v_mul_f32_e32 v17, 0xbfb8aa3b, v13
	v_mul_f32_e32 v18, 0xbfb8aa3b, v14
	v_mul_f32_e32 v19, 0xbfb8aa3b, v15
	v_exp_f32_e32 v16, v16
	v_exp_f32_e32 v17, v17
	v_exp_f32_e32 v18, v18
	v_exp_f32_e32 v19, v19
	v_lshlrev_b32_e32 v20, 16, v114
	v_and_b32_e32 v21, 0xffff0000, v114
	v_lshlrev_b32_e32 v22, 16, v115
	v_and_b32_e32 v23, 0xffff0000, v115
	v_add_f32_e32 v16, 1.0, v16
	v_add_f32_e32 v17, 1.0, v17
	v_add_f32_e32 v18, 1.0, v18
	v_add_f32_e32 v19, 1.0, v19
	v_rcp_f32_e32 v16, v16
	v_rcp_f32_e32 v17, v17
	v_rcp_f32_e32 v18, v18
	v_rcp_f32_e32 v19, v19
	v_sub_f32_e32 v20, v20, v227
	v_sub_f32_e32 v21, v21, v227
	v_sub_f32_e32 v22, v22, v227
	v_sub_f32_e32 v23, v23, v227
	v_mul_f32_e32 v20, v20, v228
	v_mul_f32_e32 v21, v21, v228
	v_mul_f32_e32 v22, v22, v228
	v_mul_f32_e32 v23, v23, v228
	v_mul_f32_e32 v12, v12, v16
	v_mul_f32_e32 v13, v13, v17
	v_mul_f32_e32 v14, v14, v18
	v_mul_f32_e32 v15, v15, v19
	v_mul_f32_e32 v20, v20, v96
	v_mul_f32_e32 v21, v21, v97
	v_mul_f32_e32 v22, v22, v98
	v_mul_f32_e32 v23, v23, v99
	v_mul_f32_e32 v20, v20, v12
	v_mul_f32_e32 v21, v21, v13
	v_mul_f32_e32 v22, v22, v14
	v_mul_f32_e32 v23, v23, v15
	v_cvt_pk_bf16_f32 v20, v20, v21
	v_cvt_pk_bf16_f32 v21, v22, v23
	global_store_dwordx2 v204, v[20:21], s[30:31] offset:736
	s_waitcnt vmcnt(29)
	v_lshlrev_b32_e32 v12, 16, v40
	v_and_b32_e32 v13, 0xffff0000, v40
	v_lshlrev_b32_e32 v14, 16, v41
	v_and_b32_e32 v15, 0xffff0000, v41
	v_mul_f32_e32 v16, 0xbfb8aa3b, v12
	v_mul_f32_e32 v17, 0xbfb8aa3b, v13
	v_mul_f32_e32 v18, 0xbfb8aa3b, v14
	v_mul_f32_e32 v19, 0xbfb8aa3b, v15
	v_exp_f32_e32 v16, v16
	v_exp_f32_e32 v17, v17
	v_exp_f32_e32 v18, v18
	v_exp_f32_e32 v19, v19
	v_lshlrev_b32_e32 v20, 16, v116
	v_and_b32_e32 v21, 0xffff0000, v116
	v_lshlrev_b32_e32 v22, 16, v117
	v_and_b32_e32 v23, 0xffff0000, v117
	v_add_f32_e32 v16, 1.0, v16
	v_add_f32_e32 v17, 1.0, v17
	v_add_f32_e32 v18, 1.0, v18
	v_add_f32_e32 v19, 1.0, v19
	v_rcp_f32_e32 v16, v16
	v_rcp_f32_e32 v17, v17
	v_rcp_f32_e32 v18, v18
	v_rcp_f32_e32 v19, v19
	v_sub_f32_e32 v20, v20, v227
	v_sub_f32_e32 v21, v21, v227
	v_sub_f32_e32 v22, v22, v227
	v_sub_f32_e32 v23, v23, v227
	v_mul_f32_e32 v20, v20, v228
	v_mul_f32_e32 v21, v21, v228
	v_mul_f32_e32 v22, v22, v228
	v_mul_f32_e32 v23, v23, v228
	v_mul_f32_e32 v12, v12, v16
	v_mul_f32_e32 v13, v13, v17
	v_mul_f32_e32 v14, v14, v18
	v_mul_f32_e32 v15, v15, v19
	v_mul_f32_e32 v20, v20, v132
	v_mul_f32_e32 v21, v21, v133
	v_mul_f32_e32 v22, v22, v134
	v_mul_f32_e32 v23, v23, v135
	v_mul_f32_e32 v20, v20, v12
	v_mul_f32_e32 v21, v21, v13
	v_mul_f32_e32 v22, v22, v14
	v_mul_f32_e32 v23, v23, v15
	v_cvt_pk_bf16_f32 v20, v20, v21
	v_cvt_pk_bf16_f32 v21, v22, v23
	global_store_dwordx2 v204, v[20:21], s[30:31] offset:768
	s_waitcnt vmcnt(27)
	v_lshlrev_b32_e32 v12, 16, v42
	v_and_b32_e32 v13, 0xffff0000, v42
	v_lshlrev_b32_e32 v14, 16, v43
	v_and_b32_e32 v15, 0xffff0000, v43
	v_mul_f32_e32 v16, 0xbfb8aa3b, v12
	v_mul_f32_e32 v17, 0xbfb8aa3b, v13
	v_mul_f32_e32 v18, 0xbfb8aa3b, v14
	v_mul_f32_e32 v19, 0xbfb8aa3b, v15
	v_exp_f32_e32 v16, v16
	v_exp_f32_e32 v17, v17
	v_exp_f32_e32 v18, v18
	v_exp_f32_e32 v19, v19
	v_lshlrev_b32_e32 v20, 16, v118
	v_and_b32_e32 v21, 0xffff0000, v118
	v_lshlrev_b32_e32 v22, 16, v119
	v_and_b32_e32 v23, 0xffff0000, v119
	v_add_f32_e32 v16, 1.0, v16
	v_add_f32_e32 v17, 1.0, v17
	v_add_f32_e32 v18, 1.0, v18
	v_add_f32_e32 v19, 1.0, v19
	v_rcp_f32_e32 v16, v16
	v_rcp_f32_e32 v17, v17
	v_rcp_f32_e32 v18, v18
	v_rcp_f32_e32 v19, v19
	v_sub_f32_e32 v20, v20, v227
	v_sub_f32_e32 v21, v21, v227
	v_sub_f32_e32 v22, v22, v227
	v_sub_f32_e32 v23, v23, v227
	v_mul_f32_e32 v20, v20, v228
	v_mul_f32_e32 v21, v21, v228
	v_mul_f32_e32 v22, v22, v228
	v_mul_f32_e32 v23, v23, v228
	v_mul_f32_e32 v12, v12, v16
	v_mul_f32_e32 v13, v13, v17
	v_mul_f32_e32 v14, v14, v18
	v_mul_f32_e32 v15, v15, v19
	v_mul_f32_e32 v20, v20, v136
	v_mul_f32_e32 v21, v21, v137
	v_mul_f32_e32 v22, v22, v138
	v_mul_f32_e32 v23, v23, v139
	v_mul_f32_e32 v20, v20, v12
	v_mul_f32_e32 v21, v21, v13
	v_mul_f32_e32 v22, v22, v14
	v_mul_f32_e32 v23, v23, v15
	v_cvt_pk_bf16_f32 v20, v20, v21
	v_cvt_pk_bf16_f32 v21, v22, v23
	global_store_dwordx2 v204, v[20:21], s[30:31] offset:800
	s_waitcnt vmcnt(25)
	v_lshlrev_b32_e32 v12, 16, v44
	v_and_b32_e32 v13, 0xffff0000, v44
	v_lshlrev_b32_e32 v14, 16, v45
	v_and_b32_e32 v15, 0xffff0000, v45
	v_mul_f32_e32 v16, 0xbfb8aa3b, v12
	v_mul_f32_e32 v17, 0xbfb8aa3b, v13
	v_mul_f32_e32 v18, 0xbfb8aa3b, v14
	v_mul_f32_e32 v19, 0xbfb8aa3b, v15
	v_exp_f32_e32 v16, v16
	v_exp_f32_e32 v17, v17
	v_exp_f32_e32 v18, v18
	v_exp_f32_e32 v19, v19
	v_lshlrev_b32_e32 v20, 16, v120
	v_and_b32_e32 v21, 0xffff0000, v120
	v_lshlrev_b32_e32 v22, 16, v121
	v_and_b32_e32 v23, 0xffff0000, v121
	v_add_f32_e32 v16, 1.0, v16
	v_add_f32_e32 v17, 1.0, v17
	v_add_f32_e32 v18, 1.0, v18
	v_add_f32_e32 v19, 1.0, v19
	v_rcp_f32_e32 v16, v16
	v_rcp_f32_e32 v17, v17
	v_rcp_f32_e32 v18, v18
	v_rcp_f32_e32 v19, v19
	v_sub_f32_e32 v20, v20, v227
	v_sub_f32_e32 v21, v21, v227
	v_sub_f32_e32 v22, v22, v227
	v_sub_f32_e32 v23, v23, v227
	v_mul_f32_e32 v20, v20, v228
	v_mul_f32_e32 v21, v21, v228
	v_mul_f32_e32 v22, v22, v228
	v_mul_f32_e32 v23, v23, v228
	v_mul_f32_e32 v12, v12, v16
	v_mul_f32_e32 v13, v13, v17
	v_mul_f32_e32 v14, v14, v18
	v_mul_f32_e32 v15, v15, v19
	v_mul_f32_e32 v20, v20, v144
	v_mul_f32_e32 v21, v21, v145
	v_mul_f32_e32 v22, v22, v146
	v_mul_f32_e32 v23, v23, v147
	v_mul_f32_e32 v20, v20, v12
	v_mul_f32_e32 v21, v21, v13
	v_mul_f32_e32 v22, v22, v14
	v_mul_f32_e32 v23, v23, v15
	v_cvt_pk_bf16_f32 v20, v20, v21
	v_cvt_pk_bf16_f32 v21, v22, v23
	global_store_dwordx2 v204, v[20:21], s[30:31] offset:832
	s_waitcnt vmcnt(23)
	v_lshlrev_b32_e32 v12, 16, v46
	v_and_b32_e32 v13, 0xffff0000, v46
	v_lshlrev_b32_e32 v14, 16, v47
	v_and_b32_e32 v15, 0xffff0000, v47
	v_mul_f32_e32 v16, 0xbfb8aa3b, v12
	v_mul_f32_e32 v17, 0xbfb8aa3b, v13
	v_mul_f32_e32 v18, 0xbfb8aa3b, v14
	v_mul_f32_e32 v19, 0xbfb8aa3b, v15
	v_exp_f32_e32 v16, v16
	v_exp_f32_e32 v17, v17
	v_exp_f32_e32 v18, v18
	v_exp_f32_e32 v19, v19
	v_lshlrev_b32_e32 v20, 16, v122
	v_and_b32_e32 v21, 0xffff0000, v122
	v_lshlrev_b32_e32 v22, 16, v123
	v_and_b32_e32 v23, 0xffff0000, v123
	v_add_f32_e32 v16, 1.0, v16
	v_add_f32_e32 v17, 1.0, v17
	v_add_f32_e32 v18, 1.0, v18
	v_add_f32_e32 v19, 1.0, v19
	v_rcp_f32_e32 v16, v16
	v_rcp_f32_e32 v17, v17
	v_rcp_f32_e32 v18, v18
	v_rcp_f32_e32 v19, v19
	v_sub_f32_e32 v20, v20, v227
	v_sub_f32_e32 v21, v21, v227
	v_sub_f32_e32 v22, v22, v227
	v_sub_f32_e32 v23, v23, v227
	v_mul_f32_e32 v20, v20, v228
	v_mul_f32_e32 v21, v21, v228
	v_mul_f32_e32 v22, v22, v228
	v_mul_f32_e32 v23, v23, v228
	v_mul_f32_e32 v12, v12, v16
	v_mul_f32_e32 v13, v13, v17
	v_mul_f32_e32 v14, v14, v18
	v_mul_f32_e32 v15, v15, v19
	v_mul_f32_e32 v20, v20, v148
	v_mul_f32_e32 v21, v21, v149
	v_mul_f32_e32 v22, v22, v150
	v_mul_f32_e32 v23, v23, v151
	v_mul_f32_e32 v20, v20, v12
	v_mul_f32_e32 v21, v21, v13
	v_mul_f32_e32 v22, v22, v14
	v_mul_f32_e32 v23, v23, v15
	v_cvt_pk_bf16_f32 v20, v20, v21
	v_cvt_pk_bf16_f32 v21, v22, v23
	global_store_dwordx2 v204, v[20:21], s[30:31] offset:864
	s_waitcnt vmcnt(21)
	v_lshlrev_b32_e32 v12, 16, v48
	v_and_b32_e32 v13, 0xffff0000, v48
	v_lshlrev_b32_e32 v14, 16, v49
	v_and_b32_e32 v15, 0xffff0000, v49
	v_mul_f32_e32 v16, 0xbfb8aa3b, v12
	v_mul_f32_e32 v17, 0xbfb8aa3b, v13
	v_mul_f32_e32 v18, 0xbfb8aa3b, v14
	v_mul_f32_e32 v19, 0xbfb8aa3b, v15
	v_exp_f32_e32 v16, v16
	v_exp_f32_e32 v17, v17
	v_exp_f32_e32 v18, v18
	v_exp_f32_e32 v19, v19
	v_lshlrev_b32_e32 v20, 16, v124
	v_and_b32_e32 v21, 0xffff0000, v124
	v_lshlrev_b32_e32 v22, 16, v125
	v_and_b32_e32 v23, 0xffff0000, v125
	v_add_f32_e32 v16, 1.0, v16
	v_add_f32_e32 v17, 1.0, v17
	v_add_f32_e32 v18, 1.0, v18
	v_add_f32_e32 v19, 1.0, v19
	v_rcp_f32_e32 v16, v16
	v_rcp_f32_e32 v17, v17
	v_rcp_f32_e32 v18, v18
	v_rcp_f32_e32 v19, v19
	v_sub_f32_e32 v20, v20, v227
	v_sub_f32_e32 v21, v21, v227
	v_sub_f32_e32 v22, v22, v227
	v_sub_f32_e32 v23, v23, v227
	v_mul_f32_e32 v20, v20, v228
	v_mul_f32_e32 v21, v21, v228
	v_mul_f32_e32 v22, v22, v228
	v_mul_f32_e32 v23, v23, v228
	v_mul_f32_e32 v12, v12, v16
	v_mul_f32_e32 v13, v13, v17
	v_mul_f32_e32 v14, v14, v18
	v_mul_f32_e32 v15, v15, v19
	v_mul_f32_e32 v20, v20, v152
	v_mul_f32_e32 v21, v21, v153
	v_mul_f32_e32 v22, v22, v154
	v_mul_f32_e32 v23, v23, v155
	v_mul_f32_e32 v20, v20, v12
	v_mul_f32_e32 v21, v21, v13
	v_mul_f32_e32 v22, v22, v14
	v_mul_f32_e32 v23, v23, v15
	v_cvt_pk_bf16_f32 v20, v20, v21
	v_cvt_pk_bf16_f32 v21, v22, v23
	global_store_dwordx2 v204, v[20:21], s[30:31] offset:896
	s_waitcnt vmcnt(19)
	v_lshlrev_b32_e32 v12, 16, v50
	v_and_b32_e32 v13, 0xffff0000, v50
	v_lshlrev_b32_e32 v14, 16, v51
	v_and_b32_e32 v15, 0xffff0000, v51
	v_mul_f32_e32 v16, 0xbfb8aa3b, v12
	v_mul_f32_e32 v17, 0xbfb8aa3b, v13
	v_mul_f32_e32 v18, 0xbfb8aa3b, v14
	v_mul_f32_e32 v19, 0xbfb8aa3b, v15
	v_exp_f32_e32 v16, v16
	v_exp_f32_e32 v17, v17
	v_exp_f32_e32 v18, v18
	v_exp_f32_e32 v19, v19
	v_lshlrev_b32_e32 v20, 16, v126
	v_and_b32_e32 v21, 0xffff0000, v126
	v_lshlrev_b32_e32 v22, 16, v127
	v_and_b32_e32 v23, 0xffff0000, v127
	v_add_f32_e32 v16, 1.0, v16
	v_add_f32_e32 v17, 1.0, v17
	v_add_f32_e32 v18, 1.0, v18
	v_add_f32_e32 v19, 1.0, v19
	v_rcp_f32_e32 v16, v16
	v_rcp_f32_e32 v17, v17
	v_rcp_f32_e32 v18, v18
	v_rcp_f32_e32 v19, v19
	v_sub_f32_e32 v20, v20, v227
	v_sub_f32_e32 v21, v21, v227
	v_sub_f32_e32 v22, v22, v227
	v_sub_f32_e32 v23, v23, v227
	v_mul_f32_e32 v20, v20, v228
	v_mul_f32_e32 v21, v21, v228
	v_mul_f32_e32 v22, v22, v228
	v_mul_f32_e32 v23, v23, v228
	v_mul_f32_e32 v12, v12, v16
	v_mul_f32_e32 v13, v13, v17
	v_mul_f32_e32 v14, v14, v18
	v_mul_f32_e32 v15, v15, v19
	v_mul_f32_e32 v20, v20, v156
	v_mul_f32_e32 v21, v21, v157
	v_mul_f32_e32 v22, v22, v158
	v_mul_f32_e32 v23, v23, v159
	v_mul_f32_e32 v20, v20, v12
	v_mul_f32_e32 v21, v21, v13
	v_mul_f32_e32 v22, v22, v14
	v_mul_f32_e32 v23, v23, v15
	v_cvt_pk_bf16_f32 v20, v20, v21
	v_cvt_pk_bf16_f32 v21, v22, v23
	global_store_dwordx2 v204, v[20:21], s[30:31] offset:928
	s_waitcnt vmcnt(17)
	v_lshlrev_b32_e32 v12, 16, v52
	v_and_b32_e32 v13, 0xffff0000, v52
	v_lshlrev_b32_e32 v14, 16, v53
	v_and_b32_e32 v15, 0xffff0000, v53
	v_mul_f32_e32 v16, 0xbfb8aa3b, v12
	v_mul_f32_e32 v17, 0xbfb8aa3b, v13
	v_mul_f32_e32 v18, 0xbfb8aa3b, v14
	v_mul_f32_e32 v19, 0xbfb8aa3b, v15
	v_exp_f32_e32 v16, v16
	v_exp_f32_e32 v17, v17
	v_exp_f32_e32 v18, v18
	v_exp_f32_e32 v19, v19
	v_lshlrev_b32_e32 v20, 16, v128
	v_and_b32_e32 v21, 0xffff0000, v128
	v_lshlrev_b32_e32 v22, 16, v129
	v_and_b32_e32 v23, 0xffff0000, v129
	v_add_f32_e32 v16, 1.0, v16
	v_add_f32_e32 v17, 1.0, v17
	v_add_f32_e32 v18, 1.0, v18
	v_add_f32_e32 v19, 1.0, v19
	v_rcp_f32_e32 v16, v16
	v_rcp_f32_e32 v17, v17
	v_rcp_f32_e32 v18, v18
	v_rcp_f32_e32 v19, v19
	v_sub_f32_e32 v20, v20, v227
	v_sub_f32_e32 v21, v21, v227
	v_sub_f32_e32 v22, v22, v227
	v_sub_f32_e32 v23, v23, v227
	v_mul_f32_e32 v20, v20, v228
	v_mul_f32_e32 v21, v21, v228
	v_mul_f32_e32 v22, v22, v228
	v_mul_f32_e32 v23, v23, v228
	v_mul_f32_e32 v12, v12, v16
	v_mul_f32_e32 v13, v13, v17
	v_mul_f32_e32 v14, v14, v18
	v_mul_f32_e32 v15, v15, v19
	v_mul_f32_e32 v20, v20, v160
	v_mul_f32_e32 v21, v21, v161
	v_mul_f32_e32 v22, v22, v162
	v_mul_f32_e32 v23, v23, v163
	v_mul_f32_e32 v20, v20, v12
	v_mul_f32_e32 v21, v21, v13
	v_mul_f32_e32 v22, v22, v14
	v_mul_f32_e32 v23, v23, v15
	v_cvt_pk_bf16_f32 v20, v20, v21
	v_cvt_pk_bf16_f32 v21, v22, v23
	global_store_dwordx2 v204, v[20:21], s[30:31] offset:960
	s_waitcnt vmcnt(15)
	v_lshlrev_b32_e32 v12, 16, v54
	v_and_b32_e32 v13, 0xffff0000, v54
	v_lshlrev_b32_e32 v14, 16, v55
	v_and_b32_e32 v15, 0xffff0000, v55
	v_mul_f32_e32 v16, 0xbfb8aa3b, v12
	v_mul_f32_e32 v17, 0xbfb8aa3b, v13
	v_mul_f32_e32 v18, 0xbfb8aa3b, v14
	v_mul_f32_e32 v19, 0xbfb8aa3b, v15
	v_exp_f32_e32 v16, v16
	v_exp_f32_e32 v17, v17
	v_exp_f32_e32 v18, v18
	v_exp_f32_e32 v19, v19
	v_lshlrev_b32_e32 v20, 16, v130
	v_and_b32_e32 v21, 0xffff0000, v130
	v_lshlrev_b32_e32 v22, 16, v131
	v_and_b32_e32 v23, 0xffff0000, v131
	v_add_f32_e32 v16, 1.0, v16
	v_add_f32_e32 v17, 1.0, v17
	v_add_f32_e32 v18, 1.0, v18
	v_add_f32_e32 v19, 1.0, v19
	v_rcp_f32_e32 v16, v16
	v_rcp_f32_e32 v17, v17
	v_rcp_f32_e32 v18, v18
	v_rcp_f32_e32 v19, v19
	v_sub_f32_e32 v20, v20, v227
	v_sub_f32_e32 v21, v21, v227
	v_sub_f32_e32 v22, v22, v227
	v_sub_f32_e32 v23, v23, v227
	v_mul_f32_e32 v20, v20, v228
	v_mul_f32_e32 v21, v21, v228
	v_mul_f32_e32 v22, v22, v228
	v_mul_f32_e32 v23, v23, v228
	v_mul_f32_e32 v12, v12, v16
	v_mul_f32_e32 v13, v13, v17
	v_mul_f32_e32 v14, v14, v18
	v_mul_f32_e32 v15, v15, v19
	v_mul_f32_e32 v20, v20, v164
	v_mul_f32_e32 v21, v21, v165
	v_mul_f32_e32 v22, v22, v166
	v_mul_f32_e32 v23, v23, v167
	v_mul_f32_e32 v20, v20, v12
	v_mul_f32_e32 v21, v21, v13
	v_mul_f32_e32 v22, v22, v14
	v_mul_f32_e32 v23, v23, v15
	v_cvt_pk_bf16_f32 v20, v20, v21
	v_cvt_pk_bf16_f32 v21, v22, v23
	global_store_dwordx2 v204, v[20:21], s[30:31] offset:992
	s_waitcnt vmcnt(0)
	s_add_i32 s6, s6, 1
	s_cmp_lt_i32 s6, 2
	s_cbranch_scc1 .Lintra_unit
	s_branch .LBB0_748
